# P0 gain-scaled weight transposes: 32 serialized load round trips per item batched into one; plus pipelined Mix/Res epilogues
# speedup vs baseline: 1.0804x; 1.0370x over previous
; #define LAS __attribute__((address_space(3)))
; DI void p0_transpose_item(const float* W, int K, int N, bf16* WT, const float* gk, int gumode, LAS float* scr, int item, int lane) {
;     const int nblk = N / 32, kb = item / nblk, nb = item % nblk, k0 = 64 * kb, n0 = 32 * nb;
;     const int drow0 = gumode == 0 ? n0 : ((n0 >> 7) * 256 + (n0 & 127) + (gumode == 2 ? 128 : 0));
; #pragma unroll 16
;     for (int i = 0; i < 32; ++i) { const int kk = 2 * i + (lane >> 5); float v = W[(size_t)(k0 + kk) * N + n0 + (lane & 31)]; if (gk) v *= gk[k0 + kk]; scr[kk * 33 + (lane & 31)] = v; }
.LBB0_33:
	s_mov_b64 s[14:15], 0
	v_lshl_add_u64 v[216:217], v[68:69], 0, s[14:15]
	global_load_dword v151, v[216:217], off
	v_lshl_add_u64 v[218:219], v[98:99], 0, s[14:15]
	global_load_dword v152, v[218:219], off
	v_lshl_add_u64 v[216:217], v[96:97], 0, s[14:15]
	global_load_dword v153, v[216:217], off
	v_lshl_add_u64 v[218:219], v[94:95], 0, s[14:15]
	global_load_dword v154, v[218:219], off
	v_lshl_add_u64 v[216:217], v[92:93], 0, s[14:15]
	global_load_dword v155, v[216:217], off
	v_lshl_add_u64 v[218:219], v[90:91], 0, s[14:15]
	global_load_dword v156, v[218:219], off
	v_lshl_add_u64 v[216:217], v[88:89], 0, s[14:15]
	global_load_dword v157, v[216:217], off
	v_lshl_add_u64 v[218:219], v[86:87], 0, s[14:15]
	global_load_dword v158, v[218:219], off
	v_lshl_add_u64 v[216:217], v[84:85], 0, s[14:15]
	global_load_dword v159, v[216:217], off
	v_lshl_add_u64 v[218:219], v[82:83], 0, s[14:15]
	global_load_dword v160, v[218:219], off
	v_lshl_add_u64 v[216:217], v[80:81], 0, s[14:15]
	global_load_dword v161, v[216:217], off
	v_lshl_add_u64 v[218:219], v[78:79], 0, s[14:15]
	global_load_dword v162, v[218:219], off
	v_lshl_add_u64 v[216:217], v[76:77], 0, s[14:15]
	global_load_dword v163, v[216:217], off
	v_lshl_add_u64 v[218:219], v[74:75], 0, s[14:15]
	global_load_dword v164, v[218:219], off
	v_lshl_add_u64 v[216:217], v[70:71], 0, s[14:15]
	global_load_dword v165, v[216:217], off
	v_lshl_add_u64 v[218:219], v[66:67], 0, s[14:15]
	global_load_dword v166, v[218:219], off
	global_load_dword v167, v[72:73], off offset:-120
	global_load_dword v168, v[72:73], off offset:-112
	global_load_dword v169, v[72:73], off offset:-104
	global_load_dword v170, v[72:73], off offset:-96
	global_load_dword v171, v[72:73], off offset:-88
	global_load_dword v172, v[72:73], off offset:-80
	global_load_dword v173, v[72:73], off offset:-72
	global_load_dword v174, v[72:73], off offset:-64
	global_load_dword v175, v[72:73], off offset:-56
	global_load_dword v176, v[72:73], off offset:-48
	global_load_dword v177, v[72:73], off offset:-40
	global_load_dword v178, v[72:73], off offset:-32
	global_load_dword v179, v[72:73], off offset:-24
	global_load_dword v180, v[72:73], off offset:-16
	global_load_dword v181, v[72:73], off offset:-8
	global_load_dword v182, v[72:73], off
	s_mov_b64 s[14:15], 0x58000
	v_lshl_add_u64 v[216:217], v[68:69], 0, s[14:15]
	global_load_dword v183, v[216:217], off
	v_lshl_add_u64 v[218:219], v[98:99], 0, s[14:15]
	global_load_dword v184, v[218:219], off
	v_lshl_add_u64 v[216:217], v[96:97], 0, s[14:15]
	global_load_dword v185, v[216:217], off
	v_lshl_add_u64 v[218:219], v[94:95], 0, s[14:15]
	global_load_dword v186, v[218:219], off
	v_lshl_add_u64 v[216:217], v[92:93], 0, s[14:15]
	global_load_dword v187, v[216:217], off
	v_lshl_add_u64 v[218:219], v[90:91], 0, s[14:15]
	global_load_dword v188, v[218:219], off
	v_lshl_add_u64 v[216:217], v[88:89], 0, s[14:15]
	global_load_dword v189, v[216:217], off
	v_lshl_add_u64 v[218:219], v[86:87], 0, s[14:15]
	global_load_dword v190, v[218:219], off
	v_lshl_add_u64 v[216:217], v[84:85], 0, s[14:15]
	global_load_dword v191, v[216:217], off
	v_lshl_add_u64 v[218:219], v[82:83], 0, s[14:15]
	global_load_dword v192, v[218:219], off
	v_lshl_add_u64 v[216:217], v[80:81], 0, s[14:15]
	global_load_dword v193, v[216:217], off
	v_lshl_add_u64 v[218:219], v[78:79], 0, s[14:15]
	global_load_dword v194, v[218:219], off
	v_lshl_add_u64 v[216:217], v[76:77], 0, s[14:15]
	global_load_dword v195, v[216:217], off
	v_lshl_add_u64 v[218:219], v[74:75], 0, s[14:15]
	global_load_dword v196, v[218:219], off
	v_lshl_add_u64 v[216:217], v[70:71], 0, s[14:15]
	global_load_dword v197, v[216:217], off
	v_lshl_add_u64 v[218:219], v[66:67], 0, s[14:15]
	global_load_dword v198, v[218:219], off
	v_lshl_add_u64 v[222:223], v[72:73], 0, s[8:9]
	v_add_u32_e32 v224, 0x1080, v2
	global_load_dword v199, v[222:223], off offset:-120
	s_waitcnt vmcnt(32)
; #define LAS __attribute__((address_space(3)))
; DI void p0_transpose_item(const float* W, int K, int N, bf16* WT, const float* gk, int gumode, LAS float* scr, int item, int lane) {
;     const int nblk = N / 32, kb = item / nblk, nb = item % nblk, k0 = 64 * kb, n0 = 32 * nb;
;     const int drow0 = gumode == 0 ? n0 : ((n0 >> 7) * 256 + (n0 & 127) + (gumode == 2 ? 128 : 0));
; #pragma unroll 16
;     for (int i = 0; i < 32; ++i) { const int kk = 2 * i + (lane >> 5); float v = W[(size_t)(k0 + kk) * N + n0 + (lane & 31)]; if (gk) v *= gk[k0 + kk]; scr[kk * 33 + (lane & 31)] = v; }
	v_mul_f32_e32 v151, v151, v167
	ds_write_b32 v2, v151
	global_load_dword v200, v[222:223], off offset:-112
	s_waitcnt vmcnt(32)
	v_mul_f32_e32 v152, v152, v168
	ds_write_b32 v2, v152 offset:264
	global_load_dword v201, v[222:223], off offset:-104
	s_waitcnt vmcnt(32)
	v_mul_f32_e32 v153, v153, v169
	ds_write_b32 v2, v153 offset:528
	global_load_dword v202, v[222:223], off offset:-96
	s_waitcnt vmcnt(32)
	v_mul_f32_e32 v154, v154, v170
	ds_write_b32 v2, v154 offset:792
	global_load_dword v203, v[222:223], off offset:-88
	s_waitcnt vmcnt(32)
	v_mul_f32_e32 v155, v155, v171
	ds_write_b32 v2, v155 offset:1056
	global_load_dword v204, v[222:223], off offset:-80
	s_waitcnt vmcnt(32)
	v_mul_f32_e32 v156, v156, v172
	ds_write_b32 v2, v156 offset:1320
	global_load_dword v205, v[222:223], off offset:-72
	s_waitcnt vmcnt(32)
	v_mul_f32_e32 v157, v157, v173
	ds_write_b32 v2, v157 offset:1584
	global_load_dword v206, v[222:223], off offset:-64
	s_waitcnt vmcnt(32)
	v_mul_f32_e32 v158, v158, v174
	ds_write_b32 v2, v158 offset:1848
	global_load_dword v207, v[222:223], off offset:-56
	s_waitcnt vmcnt(32)
	v_mul_f32_e32 v159, v159, v175
	ds_write_b32 v2, v159 offset:2112
	global_load_dword v208, v[222:223], off offset:-48
	s_waitcnt vmcnt(32)
	v_mul_f32_e32 v160, v160, v176
	ds_write_b32 v2, v160 offset:2376
	global_load_dword v209, v[222:223], off offset:-40
	s_waitcnt vmcnt(32)
	v_mul_f32_e32 v161, v161, v177
	ds_write_b32 v2, v161 offset:2640
	global_load_dword v210, v[222:223], off offset:-32
	s_waitcnt vmcnt(32)
	v_mul_f32_e32 v162, v162, v178
	ds_write_b32 v2, v162 offset:2904
	global_load_dword v211, v[222:223], off offset:-24
	s_waitcnt vmcnt(32)
	v_mul_f32_e32 v163, v163, v179
	ds_write_b32 v2, v163 offset:3168
	global_load_dword v212, v[222:223], off offset:-16
	s_waitcnt vmcnt(32)
	v_mul_f32_e32 v164, v164, v180
	ds_write_b32 v2, v164 offset:3432
	global_load_dword v213, v[222:223], off offset:-8
	s_waitcnt vmcnt(32)
	v_mul_f32_e32 v165, v165, v181
	ds_write_b32 v2, v165 offset:3696
	global_load_dword v214, v[222:223], off
	s_waitcnt vmcnt(32)
	v_mul_f32_e32 v166, v166, v182
	ds_write_b32 v2, v166 offset:3960
	s_waitcnt vmcnt(15)
	v_mul_f32_e32 v183, v183, v199
	ds_write_b32 v224, v183
	s_waitcnt vmcnt(14)
	v_mul_f32_e32 v184, v184, v200
	ds_write_b32 v224, v184 offset:264
	s_waitcnt vmcnt(13)
	v_mul_f32_e32 v185, v185, v201
	ds_write_b32 v224, v185 offset:528
	s_waitcnt vmcnt(12)
	v_mul_f32_e32 v186, v186, v202
	ds_write_b32 v224, v186 offset:792
	s_waitcnt vmcnt(11)
	v_mul_f32_e32 v187, v187, v203
	ds_write_b32 v224, v187 offset:1056
	s_waitcnt vmcnt(10)
	v_mul_f32_e32 v188, v188, v204
	ds_write_b32 v224, v188 offset:1320
	s_waitcnt vmcnt(9)
	v_mul_f32_e32 v189, v189, v205
	ds_write_b32 v224, v189 offset:1584
	s_waitcnt vmcnt(8)
	v_mul_f32_e32 v190, v190, v206
	ds_write_b32 v224, v190 offset:1848
	s_waitcnt vmcnt(7)
	v_mul_f32_e32 v191, v191, v207
	ds_write_b32 v224, v191 offset:2112
	s_waitcnt vmcnt(6)
	v_mul_f32_e32 v192, v192, v208
	ds_write_b32 v224, v192 offset:2376
	s_waitcnt vmcnt(5)
	v_mul_f32_e32 v193, v193, v209
	ds_write_b32 v224, v193 offset:2640
	s_waitcnt vmcnt(4)
	v_mul_f32_e32 v194, v194, v210
	ds_write_b32 v224, v194 offset:2904
	s_waitcnt vmcnt(3)
	v_mul_f32_e32 v195, v195, v211
	ds_write_b32 v224, v195 offset:3168
	s_waitcnt vmcnt(2)
	v_mul_f32_e32 v196, v196, v212
	ds_write_b32 v224, v196 offset:3432
	s_waitcnt vmcnt(1)
	v_mul_f32_e32 v197, v197, v213
	ds_write_b32 v224, v197 offset:3696
	s_waitcnt vmcnt(0)
	v_mul_f32_e32 v198, v198, v214
	ds_write_b32 v224, v198 offset:3960

; #define LAS __attribute__((address_space(3)))
; #define LDS_WAIT() asm volatile("s_waitcnt lgkmcnt(0)" ::: "memory")
; DI void p0_transpose_item(const float* W, int K, int N, bf16* WT, const float* gk, int gumode, LAS float* scr, int item, int lane) {
;     const int nblk = N / 32, kb = item / nblk, nb = item % nblk, k0 = 64 * kb, n0 = 32 * nb;
;     const int drow0 = gumode == 0 ? n0 : ((n0 >> 7) * 256 + (n0 & 127) + (gumode == 2 ? 128 : 0));
; #pragma unroll 16
;     for (int i = 0; i < 32; ++i) { const int kk = 2 * i + (lane >> 5); float v = W[(size_t)(k0 + kk) * N + n0 + (lane & 31)]; if (gk) v *= gk[k0 + kk]; scr[kk * 33 + (lane & 31)] = v; }
;     LDS_WAIT(); asm volatile("" ::: "memory");
.LBB0_115:
	s_mov_b64 s[38:39], 0
	v_lshl_add_u64 v[216:217], v[98:99], 0, s[38:39]
	global_load_dword v152, v[216:217], off
	v_lshl_add_u64 v[218:219], v[96:97], 0, s[38:39]
	global_load_dword v153, v[218:219], off
	v_lshl_add_u64 v[216:217], v[94:95], 0, s[38:39]
	global_load_dword v154, v[216:217], off
	v_lshl_add_u64 v[218:219], v[92:93], 0, s[38:39]
	global_load_dword v155, v[218:219], off
	v_lshl_add_u64 v[216:217], v[90:91], 0, s[38:39]
	global_load_dword v156, v[216:217], off
	v_lshl_add_u64 v[218:219], v[88:89], 0, s[38:39]
	global_load_dword v157, v[218:219], off
	v_lshl_add_u64 v[216:217], v[86:87], 0, s[38:39]
	global_load_dword v158, v[216:217], off
	v_lshl_add_u64 v[218:219], v[84:85], 0, s[38:39]
	global_load_dword v159, v[218:219], off
	v_lshl_add_u64 v[216:217], v[82:83], 0, s[38:39]
	global_load_dword v160, v[216:217], off
	v_lshl_add_u64 v[218:219], v[80:81], 0, s[38:39]
	global_load_dword v161, v[218:219], off
	v_lshl_add_u64 v[216:217], v[78:79], 0, s[38:39]
	global_load_dword v162, v[216:217], off
	v_lshl_add_u64 v[218:219], v[76:77], 0, s[38:39]
	global_load_dword v163, v[218:219], off
	v_lshl_add_u64 v[216:217], v[74:75], 0, s[38:39]
	global_load_dword v164, v[216:217], off
	v_lshl_add_u64 v[218:219], v[72:73], 0, s[38:39]
	global_load_dword v165, v[218:219], off
	v_lshl_add_u64 v[216:217], v[70:71], 0, s[38:39]
	global_load_dword v166, v[216:217], off
	v_lshl_add_u64 v[218:219], v[66:67], 0, s[38:39]
	global_load_dword v167, v[218:219], off
	v_lshl_add_u64 v[220:221], s[42:43], 0, v[100:101]
	v_lshl_add_u64 v[222:223], s[42:43], 0, v[68:69]
	global_load_dword v168, v[220:221], off
	global_load_dword v169, v[222:223], off offset:8
	global_load_dword v170, v[222:223], off offset:16
	global_load_dword v171, v[222:223], off offset:24
	global_load_dword v172, v[222:223], off offset:32
	global_load_dword v173, v[222:223], off offset:40
	global_load_dword v174, v[222:223], off offset:48
	global_load_dword v175, v[222:223], off offset:56
	global_load_dword v176, v[222:223], off offset:64
	global_load_dword v177, v[222:223], off offset:72
	global_load_dword v178, v[222:223], off offset:80
	global_load_dword v179, v[222:223], off offset:88
	global_load_dword v180, v[222:223], off offset:96
	global_load_dword v181, v[222:223], off offset:104
	global_load_dword v182, v[222:223], off offset:112
	global_load_dword v183, v[222:223], off offset:120
	s_mov_b64 s[38:39], 0xa0000
	v_lshl_add_u64 v[216:217], v[98:99], 0, s[38:39]
	global_load_dword v184, v[216:217], off
	v_lshl_add_u64 v[218:219], v[96:97], 0, s[38:39]
	global_load_dword v185, v[218:219], off
	v_lshl_add_u64 v[216:217], v[94:95], 0, s[38:39]
	global_load_dword v186, v[216:217], off
	v_lshl_add_u64 v[218:219], v[92:93], 0, s[38:39]
	global_load_dword v187, v[218:219], off
	v_lshl_add_u64 v[216:217], v[90:91], 0, s[38:39]
	global_load_dword v188, v[216:217], off
	v_lshl_add_u64 v[218:219], v[88:89], 0, s[38:39]
	global_load_dword v189, v[218:219], off
	v_lshl_add_u64 v[216:217], v[86:87], 0, s[38:39]
	global_load_dword v190, v[216:217], off
	v_lshl_add_u64 v[218:219], v[84:85], 0, s[38:39]
	global_load_dword v191, v[218:219], off
	v_lshl_add_u64 v[216:217], v[82:83], 0, s[38:39]
	global_load_dword v192, v[216:217], off
	v_lshl_add_u64 v[218:219], v[80:81], 0, s[38:39]
	global_load_dword v193, v[218:219], off
	v_lshl_add_u64 v[216:217], v[78:79], 0, s[38:39]
	global_load_dword v194, v[216:217], off
	v_lshl_add_u64 v[218:219], v[76:77], 0, s[38:39]
	global_load_dword v195, v[218:219], off
	v_lshl_add_u64 v[216:217], v[74:75], 0, s[38:39]
	global_load_dword v196, v[216:217], off
	v_lshl_add_u64 v[218:219], v[72:73], 0, s[38:39]
	global_load_dword v197, v[218:219], off
	v_lshl_add_u64 v[216:217], v[70:71], 0, s[38:39]
	global_load_dword v198, v[216:217], off
	v_lshl_add_u64 v[218:219], v[66:67], 0, s[38:39]
	global_load_dword v199, v[218:219], off
	s_add_u32 s42, s42, 0x80
	s_addc_u32 s43, s43, 0
	v_lshl_add_u64 v[224:225], s[42:43], 0, v[100:101]
	v_lshl_add_u64 v[226:227], s[42:43], 0, v[68:69]
	v_add_u32_e32 v228, 0x1080, v2
	global_load_dword v200, v[224:225], off
	s_waitcnt vmcnt(32)
; DI void p0_transpose_item(const float* W, int K, int N, bf16* WT, const float* gk, int gumode, LAS float* scr, int item, int lane) {
;     ...
;     for (int i = 0; i < 32; ++i) { const int kk = 2 * i + (lane >> 5); float v = W[(size_t)(k0 + kk) * N + n0 + (lane & 31)]; if (gk) v *= gk[k0 + kk]; scr[kk * 33 + (lane & 31)] = v; }
	v_mul_f32_e32 v152, v152, v168
	ds_write_b32 v2, v152
	global_load_dword v201, v[226:227], off offset:8
	s_waitcnt vmcnt(32)
	v_mul_f32_e32 v153, v153, v169
	ds_write_b32 v2, v153 offset:264
	global_load_dword v202, v[226:227], off offset:16
	s_waitcnt vmcnt(32)
	v_mul_f32_e32 v154, v154, v170
	ds_write_b32 v2, v154 offset:528
	global_load_dword v203, v[226:227], off offset:24
	s_waitcnt vmcnt(32)
	v_mul_f32_e32 v155, v155, v171
	ds_write_b32 v2, v155 offset:792
	global_load_dword v204, v[226:227], off offset:32
	s_waitcnt vmcnt(32)
	v_mul_f32_e32 v156, v156, v172
	ds_write_b32 v2, v156 offset:1056
	global_load_dword v205, v[226:227], off offset:40
	s_waitcnt vmcnt(32)
	v_mul_f32_e32 v157, v157, v173
	ds_write_b32 v2, v157 offset:1320
	global_load_dword v206, v[226:227], off offset:48
	s_waitcnt vmcnt(32)
	v_mul_f32_e32 v158, v158, v174
	ds_write_b32 v2, v158 offset:1584
	global_load_dword v207, v[226:227], off offset:56
	s_waitcnt vmcnt(32)
	v_mul_f32_e32 v159, v159, v175
	ds_write_b32 v2, v159 offset:1848
	global_load_dword v208, v[226:227], off offset:64
	s_waitcnt vmcnt(32)
	v_mul_f32_e32 v160, v160, v176
	ds_write_b32 v2, v160 offset:2112
	global_load_dword v209, v[226:227], off offset:72
	s_waitcnt vmcnt(32)
	v_mul_f32_e32 v161, v161, v177
	ds_write_b32 v2, v161 offset:2376
	global_load_dword v210, v[226:227], off offset:80
	s_waitcnt vmcnt(32)
	v_mul_f32_e32 v162, v162, v178
	ds_write_b32 v2, v162 offset:2640
	global_load_dword v211, v[226:227], off offset:88
	s_waitcnt vmcnt(32)
	v_mul_f32_e32 v163, v163, v179
	ds_write_b32 v2, v163 offset:2904
	global_load_dword v212, v[226:227], off offset:96
	s_waitcnt vmcnt(32)
	v_mul_f32_e32 v164, v164, v180
	ds_write_b32 v2, v164 offset:3168
	global_load_dword v213, v[226:227], off offset:104
	s_waitcnt vmcnt(32)
	v_mul_f32_e32 v165, v165, v181
	ds_write_b32 v2, v165 offset:3432
	global_load_dword v214, v[226:227], off offset:112
	s_waitcnt vmcnt(32)
	v_mul_f32_e32 v166, v166, v182
	ds_write_b32 v2, v166 offset:3696
	global_load_dword v215, v[226:227], off offset:120
	s_waitcnt vmcnt(32)
	v_mul_f32_e32 v167, v167, v183
	ds_write_b32 v2, v167 offset:3960
	s_waitcnt vmcnt(15)
	v_mul_f32_e32 v184, v184, v200
	ds_write_b32 v228, v184
	s_waitcnt vmcnt(14)
	v_mul_f32_e32 v185, v185, v201
	ds_write_b32 v228, v185 offset:264
	s_waitcnt vmcnt(13)
	v_mul_f32_e32 v186, v186, v202
	ds_write_b32 v228, v186 offset:528
	s_waitcnt vmcnt(12)
	v_mul_f32_e32 v187, v187, v203
	ds_write_b32 v228, v187 offset:792
	s_waitcnt vmcnt(11)
	v_mul_f32_e32 v188, v188, v204
	ds_write_b32 v228, v188 offset:1056
	s_waitcnt vmcnt(10)
	v_mul_f32_e32 v189, v189, v205
	ds_write_b32 v228, v189 offset:1320
	s_waitcnt vmcnt(9)
	v_mul_f32_e32 v190, v190, v206
	ds_write_b32 v228, v190 offset:1584
	s_waitcnt vmcnt(8)
	v_mul_f32_e32 v191, v191, v207
	ds_write_b32 v228, v191 offset:1848
	s_waitcnt vmcnt(7)
	v_mul_f32_e32 v192, v192, v208
	ds_write_b32 v228, v192 offset:2112
	s_waitcnt vmcnt(6)
	v_mul_f32_e32 v193, v193, v209
	ds_write_b32 v228, v193 offset:2376
	s_waitcnt vmcnt(5)
	v_mul_f32_e32 v194, v194, v210
	ds_write_b32 v228, v194 offset:2640
	s_waitcnt vmcnt(4)
	v_mul_f32_e32 v195, v195, v211
	ds_write_b32 v228, v195 offset:2904
	s_waitcnt vmcnt(3)
	v_mul_f32_e32 v196, v196, v212
	ds_write_b32 v228, v196 offset:3168
	s_waitcnt vmcnt(2)
	v_mul_f32_e32 v197, v197, v213
	ds_write_b32 v228, v197 offset:3432
	s_waitcnt vmcnt(1)
	v_mul_f32_e32 v198, v198, v214
	ds_write_b32 v228, v198 offset:3696
	s_waitcnt vmcnt(0)
	v_mul_f32_e32 v199, v199, v215
	ds_write_b32 v228, v199 offset:3960
	s_branch .LBB0_20

; DI unsigned pk2(float lo, float hi) { f32x2_t v = {lo, hi}; bf16x2_t b = __builtin_convertvector(v, bf16x2_t); return __builtin_bit_cast(unsigned, b); }
; DI float bf_lo(unsigned w) { return __uint_as_float(w << 16); }
; DI float bf_hi(unsigned w) { return __uint_as_float(w & 0xffff0000u); }
;     DI void operator()(AccRef acc, const Unit& u, int wr, int wc, int fr, int fq) const {
;         const int row0 = u.pm * BM + wr * 64 + fr, col0 = u.pn * BM + wc * 32 + 8 * fq;
; #pragma unroll
;         for (int ai = 0; ai < 2; ++ai)
; #pragma unroll
;             for (int m = 0; m < 4; ++m) {
;                 const int row = row0 + ai * HALF + m * 16;
; #pragma unroll
;                 for (int bj = 0; bj < 2; ++bj) {
;                     const size_t off = (size_t)row * DM + col0 + bj * HALF;
;                     const f32x4 v0 = acc[ai][bj][m][0], v1 = acc[ai][bj][m][1];
;                     const u32x4 a = ld16_l2(M1 + off); u32x4 w;
;                     if (MODE == 0) {
;                         w.x = pk2(bf_lo(a.x) * v0[0], bf_hi(a.x) * v0[1]); w.y = pk2(bf_lo(a.y) * v0[2], bf_hi(a.y) * v0[3]);
;                         w.z = pk2(bf_lo(a.z) * v1[0], bf_hi(a.z) * v1[1]); w.w = pk2(bf_lo(a.w) * v1[2], bf_hi(a.w) * v1[3]);
;                     } else {
;                         const u32x4 b = ld16_l2(M2 + off);
;                         w.x = pk2(bf_lo(a.x) + bf_lo(b.x) * v0[0], bf_hi(a.x) + bf_hi(b.x) * v0[1]); w.y = pk2(bf_lo(a.y) + bf_lo(b.y) * v0[2], bf_hi(a.y) + bf_hi(b.y) * v0[3]);
;                         w.z = pk2(bf_lo(a.z) + bf_lo(b.z) * v1[0], bf_hi(a.z) + bf_hi(b.z) * v1[1]); w.w = pk2(bf_lo(a.w) + bf_lo(b.w) * v1[2], bf_hi(a.w) + bf_hi(b.w) * v1[3]);
;                     }
;                     *(u32x4*)(M1 + off) = w;
.LBB0_1274:
	s_mov_b32 s19, 0x40000
	s_mov_b64 s[28:29], 0x40000
	v_lshlrev_b32_e32 v170, 11, v129
	v_lshl_add_u32 v170, v133, 1, v170
	s_lshl_b32 s98, s26, 19
	s_lshl_b32 s100, s60, 9
	s_add_u32 s98, s98, s100
	s_add_u32 s98, s54, s98
	s_addc_u32 s99, s55, 0
	global_load_dwordx4 v[172:175], v170, s[98:99] sc1
	global_load_dwordx4 v[176:179], v170, s[98:99] offset:256 sc1
	s_add_u32 s98, s98, 0x8000
	s_addc_u32 s99, s99, 0
	global_load_dwordx4 v[180:183], v170, s[98:99] sc1
	global_load_dwordx4 v[184:187], v170, s[98:99] offset:256 sc1
	s_add_u32 s98, s98, 0x8000
	s_addc_u32 s99, s99, 0
	global_load_dwordx4 v[188:191], v170, s[98:99] sc1
	global_load_dwordx4 v[192:195], v170, s[98:99] offset:256 sc1
	s_add_u32 s98, s98, 0x8000
	s_addc_u32 s99, s99, 0
	global_load_dwordx4 v[196:199], v170, s[98:99] sc1
	global_load_dwordx4 v[200:203], v170, s[98:99] offset:256 sc1
	s_add_u32 s98, s98, 0x28000
	s_addc_u32 s99, s99, 0
	global_load_dwordx4 v[204:207], v170, s[98:99] sc1
	global_load_dwordx4 v[208:211], v170, s[98:99] offset:256 sc1
	s_add_u32 s98, s98, 0x8000
	s_addc_u32 s99, s99, 0
	global_load_dwordx4 v[212:215], v170, s[98:99] sc1
	global_load_dwordx4 v[216:219], v170, s[98:99] offset:256 sc1
	s_add_u32 s98, s98, 0x8000
	s_addc_u32 s99, s99, 0
	global_load_dwordx4 v[220:223], v170, s[98:99] sc1
	global_load_dwordx4 v[224:227], v170, s[98:99] offset:256 sc1
	s_add_u32 s98, s98, 0x8000
	s_addc_u32 s99, s99, 0
	global_load_dwordx4 v[228:231], v170, s[98:99] sc1
	global_load_dwordx4 v[232:235], v170, s[98:99] offset:256 sc1
	s_sub_u32 s98, s98, 0x58000
	s_subb_u32 s99, s99, 0
	s_waitcnt vmcnt(15)
	v_lshlrev_b32_e32 v236, 16, v172
	v_and_b32_e32 v172, 0xffff0000, v172
	v_lshlrev_b32_e32 v237, 16, v173
	v_and_b32_e32 v173, 0xffff0000, v173
	v_lshlrev_b32_e32 v238, 16, v174
	v_and_b32_e32 v174, 0xffff0000, v174
	v_lshlrev_b32_e32 v239, 16, v175
	v_and_b32_e32 v175, 0xffff0000, v175
	v_mul_f32_e32 v236, v124, v236
	v_mul_f32_e32 v172, v125, v172
	v_mul_f32_e32 v237, v126, v237
	v_mul_f32_e32 v173, v127, v173
	v_mul_f32_e32 v238, v120, v238
	v_mul_f32_e32 v174, v121, v174
	v_mul_f32_e32 v239, v122, v239
	v_mul_f32_e32 v175, v123, v175
	v_cvt_pk_bf16_f32 v172, v236, v172
	v_cvt_pk_bf16_f32 v173, v237, v173
	v_cvt_pk_bf16_f32 v174, v238, v174
	v_cvt_pk_bf16_f32 v175, v239, v175
	global_store_dwordx4 v170, v[172:175], s[98:99]
	s_waitcnt vmcnt(15)
	v_lshlrev_b32_e32 v236, 16, v176
	v_and_b32_e32 v176, 0xffff0000, v176
	v_lshlrev_b32_e32 v237, 16, v177
	v_and_b32_e32 v177, 0xffff0000, v177
	v_lshlrev_b32_e32 v238, 16, v178
	v_and_b32_e32 v178, 0xffff0000, v178
	v_lshlrev_b32_e32 v239, 16, v179
	v_and_b32_e32 v179, 0xffff0000, v179
	v_mul_f32_e32 v236, v116, v236
	v_mul_f32_e32 v176, v117, v176
	v_mul_f32_e32 v237, v118, v237
	v_mul_f32_e32 v177, v119, v177
	v_mul_f32_e32 v238, v112, v238
	v_mul_f32_e32 v178, v113, v178
	v_mul_f32_e32 v239, v114, v239
	v_mul_f32_e32 v179, v115, v179
	v_cvt_pk_bf16_f32 v176, v236, v176
	v_cvt_pk_bf16_f32 v177, v237, v177
	v_cvt_pk_bf16_f32 v178, v238, v178
	v_cvt_pk_bf16_f32 v179, v239, v179
	global_store_dwordx4 v170, v[176:179], s[98:99] offset:256
	s_add_u32 s98, s98, 0x8000
	s_addc_u32 s99, s99, 0
	s_waitcnt vmcnt(15)
	v_lshlrev_b32_e32 v236, 16, v180
	v_and_b32_e32 v180, 0xffff0000, v180
	v_lshlrev_b32_e32 v237, 16, v181
	v_and_b32_e32 v181, 0xffff0000, v181
	v_lshlrev_b32_e32 v238, 16, v182
	v_and_b32_e32 v182, 0xffff0000, v182
	v_lshlrev_b32_e32 v239, 16, v183
	v_and_b32_e32 v183, 0xffff0000, v183
	v_mul_f32_e32 v236, v108, v236
	v_mul_f32_e32 v180, v109, v180
	v_mul_f32_e32 v237, v110, v237
	v_mul_f32_e32 v181, v111, v181
	v_mul_f32_e32 v238, v104, v238
	v_mul_f32_e32 v182, v105, v182
	v_mul_f32_e32 v239, v106, v239
	v_mul_f32_e32 v183, v107, v183
	v_cvt_pk_bf16_f32 v180, v236, v180
	v_cvt_pk_bf16_f32 v181, v237, v181
	v_cvt_pk_bf16_f32 v182, v238, v182
	v_cvt_pk_bf16_f32 v183, v239, v183
	global_store_dwordx4 v170, v[180:183], s[98:99]
	s_waitcnt vmcnt(15)
	v_lshlrev_b32_e32 v236, 16, v184
	v_and_b32_e32 v184, 0xffff0000, v184
	v_lshlrev_b32_e32 v237, 16, v185
	v_and_b32_e32 v185, 0xffff0000, v185
	v_lshlrev_b32_e32 v238, 16, v186
	v_and_b32_e32 v186, 0xffff0000, v186
	v_lshlrev_b32_e32 v239, 16, v187
	v_and_b32_e32 v187, 0xffff0000, v187
	v_mul_f32_e32 v236, v100, v236
	v_mul_f32_e32 v184, v101, v184
	v_mul_f32_e32 v237, v102, v237
	v_mul_f32_e32 v185, v103, v185
	v_mul_f32_e32 v238, v96, v238
	v_mul_f32_e32 v186, v97, v186
	v_mul_f32_e32 v239, v98, v239
	v_mul_f32_e32 v187, v99, v187
	v_cvt_pk_bf16_f32 v184, v236, v184
	v_cvt_pk_bf16_f32 v185, v237, v185
	v_cvt_pk_bf16_f32 v186, v238, v186
	v_cvt_pk_bf16_f32 v187, v239, v187
	global_store_dwordx4 v170, v[184:187], s[98:99] offset:256
	s_add_u32 s98, s98, 0x8000
	s_addc_u32 s99, s99, 0
	s_waitcnt vmcnt(15)
	v_lshlrev_b32_e32 v236, 16, v188
	v_and_b32_e32 v188, 0xffff0000, v188
	v_lshlrev_b32_e32 v237, 16, v189
	v_and_b32_e32 v189, 0xffff0000, v189
	v_lshlrev_b32_e32 v238, 16, v190
	v_and_b32_e32 v190, 0xffff0000, v190
	v_lshlrev_b32_e32 v239, 16, v191
	v_and_b32_e32 v191, 0xffff0000, v191
	v_mul_f32_e32 v236, v92, v236
	v_mul_f32_e32 v188, v93, v188
	v_mul_f32_e32 v237, v94, v237
	v_mul_f32_e32 v189, v95, v189
	v_mul_f32_e32 v238, v88, v238
	v_mul_f32_e32 v190, v89, v190
	v_mul_f32_e32 v239, v90, v239
	v_mul_f32_e32 v191, v91, v191
	v_cvt_pk_bf16_f32 v188, v236, v188
	v_cvt_pk_bf16_f32 v189, v237, v189
	v_cvt_pk_bf16_f32 v190, v238, v190
	v_cvt_pk_bf16_f32 v191, v239, v191
	global_store_dwordx4 v170, v[188:191], s[98:99]
	s_waitcnt vmcnt(15)
; DI unsigned pk2(float lo, float hi) { f32x2_t v = {lo, hi}; bf16x2_t b = __builtin_convertvector(v, bf16x2_t); return __builtin_bit_cast(unsigned, b); }
; DI float bf_lo(unsigned w) { return __uint_as_float(w << 16); }
; DI float bf_hi(unsigned w) { return __uint_as_float(w & 0xffff0000u); }
;     DI void operator()(AccRef acc, const Unit& u, int wr, int wc, int fr, int fq) const {
;     ...
;                 const int row = row0 + ai * HALF + m * 16;
; #pragma unroll
;                 for (int bj = 0; bj < 2; ++bj) {
;                     const size_t off = (size_t)row * DM + col0 + bj * HALF;
;                     const f32x4 v0 = acc[ai][bj][m][0], v1 = acc[ai][bj][m][1];
;                     const u32x4 a = ld16_l2(M1 + off); u32x4 w;
;                     if (MODE == 0) {
;                         w.x = pk2(bf_lo(a.x) * v0[0], bf_hi(a.x) * v0[1]); w.y = pk2(bf_lo(a.y) * v0[2], bf_hi(a.y) * v0[3]);
;                         w.z = pk2(bf_lo(a.z) * v1[0], bf_hi(a.z) * v1[1]); w.w = pk2(bf_lo(a.w) * v1[2], bf_hi(a.w) * v1[3]);
;                     } else {
;                         const u32x4 b = ld16_l2(M2 + off);
;                         w.x = pk2(bf_lo(a.x) + bf_lo(b.x) * v0[0], bf_hi(a.x) + bf_hi(b.x) * v0[1]); w.y = pk2(bf_lo(a.y) + bf_lo(b.y) * v0[2], bf_hi(a.y) + bf_hi(b.y) * v0[3]);
;                         w.z = pk2(bf_lo(a.z) + bf_lo(b.z) * v1[0], bf_hi(a.z) + bf_hi(b.z) * v1[1]); w.w = pk2(bf_lo(a.w) + bf_lo(b.w) * v1[2], bf_hi(a.w) + bf_hi(b.w) * v1[3]);
;                     }
;                     *(u32x4*)(M1 + off) = w;
	v_lshlrev_b32_e32 v236, 16, v192
	v_and_b32_e32 v192, 0xffff0000, v192
	v_lshlrev_b32_e32 v237, 16, v193
	v_and_b32_e32 v193, 0xffff0000, v193
	v_lshlrev_b32_e32 v238, 16, v194
	v_and_b32_e32 v194, 0xffff0000, v194
	v_lshlrev_b32_e32 v239, 16, v195
	v_and_b32_e32 v195, 0xffff0000, v195
	v_mul_f32_e32 v236, v84, v236
	v_mul_f32_e32 v192, v85, v192
	v_mul_f32_e32 v237, v86, v237
	v_mul_f32_e32 v193, v87, v193
	v_mul_f32_e32 v238, v80, v238
	v_mul_f32_e32 v194, v81, v194
	v_mul_f32_e32 v239, v82, v239
	v_mul_f32_e32 v195, v83, v195
	v_cvt_pk_bf16_f32 v192, v236, v192
	v_cvt_pk_bf16_f32 v193, v237, v193
	v_cvt_pk_bf16_f32 v194, v238, v194
	v_cvt_pk_bf16_f32 v195, v239, v195
	global_store_dwordx4 v170, v[192:195], s[98:99] offset:256
	s_add_u32 s98, s98, 0x8000
	s_addc_u32 s99, s99, 0
	s_waitcnt vmcnt(15)
	v_lshlrev_b32_e32 v236, 16, v196
	v_and_b32_e32 v196, 0xffff0000, v196
	v_lshlrev_b32_e32 v237, 16, v197
	v_and_b32_e32 v197, 0xffff0000, v197
	v_lshlrev_b32_e32 v238, 16, v198
	v_and_b32_e32 v198, 0xffff0000, v198
	v_lshlrev_b32_e32 v239, 16, v199
	v_and_b32_e32 v199, 0xffff0000, v199
	v_mul_f32_e32 v236, v76, v236
	v_mul_f32_e32 v196, v77, v196
	v_mul_f32_e32 v237, v78, v237
	v_mul_f32_e32 v197, v79, v197
	v_mul_f32_e32 v238, v72, v238
	v_mul_f32_e32 v198, v73, v198
	v_mul_f32_e32 v239, v74, v239
	v_mul_f32_e32 v199, v75, v199
	v_cvt_pk_bf16_f32 v196, v236, v196
	v_cvt_pk_bf16_f32 v197, v237, v197
	v_cvt_pk_bf16_f32 v198, v238, v198
	v_cvt_pk_bf16_f32 v199, v239, v199
	global_store_dwordx4 v170, v[196:199], s[98:99]
	s_waitcnt vmcnt(15)
	v_lshlrev_b32_e32 v236, 16, v200
	v_and_b32_e32 v200, 0xffff0000, v200
	v_lshlrev_b32_e32 v237, 16, v201
	v_and_b32_e32 v201, 0xffff0000, v201
	v_lshlrev_b32_e32 v238, 16, v202
	v_and_b32_e32 v202, 0xffff0000, v202
	v_lshlrev_b32_e32 v239, 16, v203
	v_and_b32_e32 v203, 0xffff0000, v203
	v_mul_f32_e32 v236, v68, v236
	v_mul_f32_e32 v200, v69, v200
	v_mul_f32_e32 v237, v70, v237
	v_mul_f32_e32 v201, v71, v201
	v_mul_f32_e32 v238, v64, v238
	v_mul_f32_e32 v202, v65, v202
	v_mul_f32_e32 v239, v66, v239
	v_mul_f32_e32 v203, v67, v203
	v_cvt_pk_bf16_f32 v200, v236, v200
	v_cvt_pk_bf16_f32 v201, v237, v201
	v_cvt_pk_bf16_f32 v202, v238, v202
	v_cvt_pk_bf16_f32 v203, v239, v203
	global_store_dwordx4 v170, v[200:203], s[98:99] offset:256
	s_add_u32 s98, s98, 0x28000
	s_addc_u32 s99, s99, 0
	s_waitcnt vmcnt(15)
	v_lshlrev_b32_e32 v236, 16, v204
	v_and_b32_e32 v204, 0xffff0000, v204
	v_lshlrev_b32_e32 v237, 16, v205
	v_and_b32_e32 v205, 0xffff0000, v205
	v_lshlrev_b32_e32 v238, 16, v206
	v_and_b32_e32 v206, 0xffff0000, v206
	v_lshlrev_b32_e32 v239, 16, v207
	v_and_b32_e32 v207, 0xffff0000, v207
	v_mul_f32_e32 v236, v60, v236
	v_mul_f32_e32 v204, v61, v204
	v_mul_f32_e32 v237, v62, v237
	v_mul_f32_e32 v205, v63, v205
	v_mul_f32_e32 v238, v56, v238
	v_mul_f32_e32 v206, v57, v206
	v_mul_f32_e32 v239, v58, v239
	v_mul_f32_e32 v207, v59, v207
	v_cvt_pk_bf16_f32 v204, v236, v204
	v_cvt_pk_bf16_f32 v205, v237, v205
	v_cvt_pk_bf16_f32 v206, v238, v206
	v_cvt_pk_bf16_f32 v207, v239, v207
	global_store_dwordx4 v170, v[204:207], s[98:99]
	s_waitcnt vmcnt(15)
	v_lshlrev_b32_e32 v236, 16, v208
	v_and_b32_e32 v208, 0xffff0000, v208
	v_lshlrev_b32_e32 v237, 16, v209
	v_and_b32_e32 v209, 0xffff0000, v209
	v_lshlrev_b32_e32 v238, 16, v210
	v_and_b32_e32 v210, 0xffff0000, v210
	v_lshlrev_b32_e32 v239, 16, v211
	v_and_b32_e32 v211, 0xffff0000, v211
	v_mul_f32_e32 v236, v52, v236
	v_mul_f32_e32 v208, v53, v208
	v_mul_f32_e32 v237, v54, v237
	v_mul_f32_e32 v209, v55, v209
	v_mul_f32_e32 v238, v48, v238
	v_mul_f32_e32 v210, v49, v210
	v_mul_f32_e32 v239, v50, v239
	v_mul_f32_e32 v211, v51, v211
	v_cvt_pk_bf16_f32 v208, v236, v208
	v_cvt_pk_bf16_f32 v209, v237, v209
	v_cvt_pk_bf16_f32 v210, v238, v210
	v_cvt_pk_bf16_f32 v211, v239, v211
	global_store_dwordx4 v170, v[208:211], s[98:99] offset:256
	s_add_u32 s98, s98, 0x8000
	s_addc_u32 s99, s99, 0
	s_waitcnt vmcnt(15)
	v_lshlrev_b32_e32 v236, 16, v212
	v_and_b32_e32 v212, 0xffff0000, v212
	v_lshlrev_b32_e32 v237, 16, v213
	v_and_b32_e32 v213, 0xffff0000, v213
	v_lshlrev_b32_e32 v238, 16, v214
	v_and_b32_e32 v214, 0xffff0000, v214
	v_lshlrev_b32_e32 v239, 16, v215
	v_and_b32_e32 v215, 0xffff0000, v215
	v_mul_f32_e32 v236, v44, v236
	v_mul_f32_e32 v212, v45, v212
	v_mul_f32_e32 v237, v46, v237
	v_mul_f32_e32 v213, v47, v213
	v_mul_f32_e32 v238, v40, v238
	v_mul_f32_e32 v214, v41, v214
	v_mul_f32_e32 v239, v42, v239
	v_mul_f32_e32 v215, v43, v215
	v_cvt_pk_bf16_f32 v212, v236, v212
	v_cvt_pk_bf16_f32 v213, v237, v213
	v_cvt_pk_bf16_f32 v214, v238, v214
	v_cvt_pk_bf16_f32 v215, v239, v215
	global_store_dwordx4 v170, v[212:215], s[98:99]
	s_waitcnt vmcnt(15)
; DI unsigned pk2(float lo, float hi) { f32x2_t v = {lo, hi}; bf16x2_t b = __builtin_convertvector(v, bf16x2_t); return __builtin_bit_cast(unsigned, b); }
; DI float bf_lo(unsigned w) { return __uint_as_float(w << 16); }
; DI float bf_hi(unsigned w) { return __uint_as_float(w & 0xffff0000u); }
;     DI void operator()(AccRef acc, const Unit& u, int wr, int wc, int fr, int fq) const {
;     ...
;                 const int row = row0 + ai * HALF + m * 16;
; #pragma unroll
;                 for (int bj = 0; bj < 2; ++bj) {
;                     const size_t off = (size_t)row * DM + col0 + bj * HALF;
;                     const f32x4 v0 = acc[ai][bj][m][0], v1 = acc[ai][bj][m][1];
;                     const u32x4 a = ld16_l2(M1 + off); u32x4 w;
;                     if (MODE == 0) {
;                         w.x = pk2(bf_lo(a.x) * v0[0], bf_hi(a.x) * v0[1]); w.y = pk2(bf_lo(a.y) * v0[2], bf_hi(a.y) * v0[3]);
;                         w.z = pk2(bf_lo(a.z) * v1[0], bf_hi(a.z) * v1[1]); w.w = pk2(bf_lo(a.w) * v1[2], bf_hi(a.w) * v1[3]);
;                     } else {
;                         const u32x4 b = ld16_l2(M2 + off);
;                         w.x = pk2(bf_lo(a.x) + bf_lo(b.x) * v0[0], bf_hi(a.x) + bf_hi(b.x) * v0[1]); w.y = pk2(bf_lo(a.y) + bf_lo(b.y) * v0[2], bf_hi(a.y) + bf_hi(b.y) * v0[3]);
;                         w.z = pk2(bf_lo(a.z) + bf_lo(b.z) * v1[0], bf_hi(a.z) + bf_hi(b.z) * v1[1]); w.w = pk2(bf_lo(a.w) + bf_lo(b.w) * v1[2], bf_hi(a.w) + bf_hi(b.w) * v1[3]);
;                     }
;                     *(u32x4*)(M1 + off) = w;
	v_lshlrev_b32_e32 v236, 16, v216
	v_and_b32_e32 v216, 0xffff0000, v216
	v_lshlrev_b32_e32 v237, 16, v217
	v_and_b32_e32 v217, 0xffff0000, v217
	v_lshlrev_b32_e32 v238, 16, v218
	v_and_b32_e32 v218, 0xffff0000, v218
	v_lshlrev_b32_e32 v239, 16, v219
	v_and_b32_e32 v219, 0xffff0000, v219
	v_mul_f32_e32 v236, v36, v236
	v_mul_f32_e32 v216, v37, v216
	v_mul_f32_e32 v237, v38, v237
	v_mul_f32_e32 v217, v39, v217
	v_mul_f32_e32 v238, v32, v238
	v_mul_f32_e32 v218, v33, v218
	v_mul_f32_e32 v239, v34, v239
	v_mul_f32_e32 v219, v35, v219
	v_cvt_pk_bf16_f32 v216, v236, v216
	v_cvt_pk_bf16_f32 v217, v237, v217
	v_cvt_pk_bf16_f32 v218, v238, v218
	v_cvt_pk_bf16_f32 v219, v239, v219
	global_store_dwordx4 v170, v[216:219], s[98:99] offset:256
	s_add_u32 s98, s98, 0x8000
	s_addc_u32 s99, s99, 0
	s_waitcnt vmcnt(15)
	v_lshlrev_b32_e32 v236, 16, v220
	v_and_b32_e32 v220, 0xffff0000, v220
	v_lshlrev_b32_e32 v237, 16, v221
	v_and_b32_e32 v221, 0xffff0000, v221
	v_lshlrev_b32_e32 v238, 16, v222
	v_and_b32_e32 v222, 0xffff0000, v222
	v_lshlrev_b32_e32 v239, 16, v223
	v_and_b32_e32 v223, 0xffff0000, v223
	v_mul_f32_e32 v236, v28, v236
	v_mul_f32_e32 v220, v29, v220
	v_mul_f32_e32 v237, v30, v237
	v_mul_f32_e32 v221, v31, v221
	v_mul_f32_e32 v238, v24, v238
	v_mul_f32_e32 v222, v25, v222
	v_mul_f32_e32 v239, v26, v239
	v_mul_f32_e32 v223, v27, v223
	v_cvt_pk_bf16_f32 v220, v236, v220
	v_cvt_pk_bf16_f32 v221, v237, v221
	v_cvt_pk_bf16_f32 v222, v238, v222
	v_cvt_pk_bf16_f32 v223, v239, v223
	global_store_dwordx4 v170, v[220:223], s[98:99]
	s_waitcnt vmcnt(15)
	v_lshlrev_b32_e32 v236, 16, v224
	v_and_b32_e32 v224, 0xffff0000, v224
	v_lshlrev_b32_e32 v237, 16, v225
	v_and_b32_e32 v225, 0xffff0000, v225
	v_lshlrev_b32_e32 v238, 16, v226
	v_and_b32_e32 v226, 0xffff0000, v226
	v_lshlrev_b32_e32 v239, 16, v227
	v_and_b32_e32 v227, 0xffff0000, v227
	v_mul_f32_e32 v236, v20, v236
	v_mul_f32_e32 v224, v21, v224
	v_mul_f32_e32 v237, v22, v237
	v_mul_f32_e32 v225, v23, v225
	v_mul_f32_e32 v238, v16, v238
	v_mul_f32_e32 v226, v17, v226
	v_mul_f32_e32 v239, v18, v239
	v_mul_f32_e32 v227, v19, v227
	v_cvt_pk_bf16_f32 v224, v236, v224
	v_cvt_pk_bf16_f32 v225, v237, v225
	v_cvt_pk_bf16_f32 v226, v238, v226
	v_cvt_pk_bf16_f32 v227, v239, v227
	global_store_dwordx4 v170, v[224:227], s[98:99] offset:256
	s_add_u32 s98, s98, 0x8000
	s_addc_u32 s99, s99, 0
	s_waitcnt vmcnt(15)
	v_lshlrev_b32_e32 v236, 16, v228
	v_and_b32_e32 v228, 0xffff0000, v228
	v_lshlrev_b32_e32 v237, 16, v229
	v_and_b32_e32 v229, 0xffff0000, v229
	v_lshlrev_b32_e32 v238, 16, v230
	v_and_b32_e32 v230, 0xffff0000, v230
	v_lshlrev_b32_e32 v239, 16, v231
	v_and_b32_e32 v231, 0xffff0000, v231
	v_mul_f32_e32 v236, v12, v236
	v_mul_f32_e32 v228, v13, v228
	v_mul_f32_e32 v237, v14, v237
	v_mul_f32_e32 v229, v15, v229
	v_mul_f32_e32 v238, v8, v238
	v_mul_f32_e32 v230, v9, v230
	v_mul_f32_e32 v239, v10, v239
	v_mul_f32_e32 v231, v11, v231
	v_cvt_pk_bf16_f32 v228, v236, v228
	v_cvt_pk_bf16_f32 v229, v237, v229
	v_cvt_pk_bf16_f32 v230, v238, v230
	v_cvt_pk_bf16_f32 v231, v239, v231
	global_store_dwordx4 v170, v[228:231], s[98:99]
	s_waitcnt vmcnt(15)
	v_lshlrev_b32_e32 v236, 16, v232
	v_and_b32_e32 v232, 0xffff0000, v232
	v_lshlrev_b32_e32 v237, 16, v233
	v_and_b32_e32 v233, 0xffff0000, v233
	v_lshlrev_b32_e32 v238, 16, v234
	v_and_b32_e32 v234, 0xffff0000, v234
	v_lshlrev_b32_e32 v239, 16, v235
	v_and_b32_e32 v235, 0xffff0000, v235
	v_mul_f32_e32 v236, v4, v236
	v_mul_f32_e32 v232, v5, v232
	v_mul_f32_e32 v237, v6, v237
	v_mul_f32_e32 v233, v7, v233
	v_mul_f32_e32 v238, v0, v238
	v_mul_f32_e32 v234, v1, v234
	v_mul_f32_e32 v239, v2, v239
	v_mul_f32_e32 v235, v3, v235
	v_cvt_pk_bf16_f32 v232, v236, v232
	v_cvt_pk_bf16_f32 v233, v237, v233
	v_cvt_pk_bf16_f32 v234, v238, v234
	v_cvt_pk_bf16_f32 v235, v239, v235
	global_store_dwordx4 v170, v[232:235], s[98:99] offset:256
	s_andn2_b64 vcc, exec, s[4:5]
	s_mov_b64 s[4:5], -1
	s_cbranch_vccnz .LBB0_1263
	s_andn2_b64 vcc, exec, s[0:1]
	s_cbranch_vccnz .LBB0_1262
	s_barrier
	s_branch .LBB0_1262

; DI unsigned pk2(float lo, float hi) { f32x2_t v = {lo, hi}; bf16x2_t b = __builtin_convertvector(v, bf16x2_t); return __builtin_bit_cast(unsigned, b); }
; DI float bf_lo(unsigned w) { return __uint_as_float(w << 16); }
; DI float bf_hi(unsigned w) { return __uint_as_float(w & 0xffff0000u); }
;     DI void operator()(AccRef acc, const Unit& u, int wr, int wc, int fr, int fq) const {
;         const int row0 = u.pm * BM + wr * 64 + fr, col0 = u.pn * BM + wc * 32 + 8 * fq;
; #pragma unroll
;         for (int ai = 0; ai < 2; ++ai)
; #pragma unroll
;             for (int m = 0; m < 4; ++m) {
;                 const int row = row0 + ai * HALF + m * 16;
; #pragma unroll
;                 for (int bj = 0; bj < 2; ++bj) {
;                     const size_t off = (size_t)row * DM + col0 + bj * HALF;
;                     const f32x4 v0 = acc[ai][bj][m][0], v1 = acc[ai][bj][m][1];
;                     const u32x4 a = ld16_l2(M1 + off); u32x4 w;
;                     if (MODE == 0) {
;                         w.x = pk2(bf_lo(a.x) * v0[0], bf_hi(a.x) * v0[1]); w.y = pk2(bf_lo(a.y) * v0[2], bf_hi(a.y) * v0[3]);
;                         w.z = pk2(bf_lo(a.z) * v1[0], bf_hi(a.z) * v1[1]); w.w = pk2(bf_lo(a.w) * v1[2], bf_hi(a.w) * v1[3]);
;                     } else {
;                         const u32x4 b = ld16_l2(M2 + off);
;                         w.x = pk2(bf_lo(a.x) + bf_lo(b.x) * v0[0], bf_hi(a.x) + bf_hi(b.x) * v0[1]); w.y = pk2(bf_lo(a.y) + bf_lo(b.y) * v0[2], bf_hi(a.y) + bf_hi(b.y) * v0[3]);
;                         w.z = pk2(bf_lo(a.z) + bf_lo(b.z) * v1[0], bf_hi(a.z) + bf_hi(b.z) * v1[1]); w.w = pk2(bf_lo(a.w) + bf_lo(b.w) * v1[2], bf_hi(a.w) + bf_hi(b.w) * v1[3]);
;                     }
;                     *(u32x4*)(M1 + off) = w;
.LBB0_1322:
	v_lshlrev_b32_e32 v170, 11, v156
	v_lshl_add_u32 v170, v158, 1, v170
	v_add_u32_e32 v171, 0x40000, v170
	s_lshl_b32 s98, s28, 19
	s_lshl_b32 s100, s52, 9
	s_add_u32 s30, s98, s100
	s_add_u32 s98, s54, s30
	s_addc_u32 s99, s55, 0
	s_add_u32 s100, s80, s30
	s_addc_u32 s101, s81, 0
	global_load_dwordx4 v[172:175], v170, s[98:99] sc1
	global_load_dwordx4 v[204:207], v170, s[100:101] sc1
	global_load_dwordx4 v[176:179], v170, s[98:99] offset:256 sc1
	global_load_dwordx4 v[208:211], v170, s[100:101] offset:256 sc1
	s_add_u32 s98, s98, 0x8000
	s_addc_u32 s99, s99, 0
	s_add_u32 s100, s100, 0x8000
	s_addc_u32 s101, s101, 0
	global_load_dwordx4 v[180:183], v170, s[98:99] sc1
	global_load_dwordx4 v[212:215], v170, s[100:101] sc1
	global_load_dwordx4 v[184:187], v170, s[98:99] offset:256 sc1
	global_load_dwordx4 v[216:219], v170, s[100:101] offset:256 sc1
	s_add_u32 s98, s98, 0x8000
	s_addc_u32 s99, s99, 0
	s_add_u32 s100, s100, 0x8000
	s_addc_u32 s101, s101, 0
	global_load_dwordx4 v[188:191], v170, s[98:99] sc1
	global_load_dwordx4 v[220:223], v170, s[100:101] sc1
	global_load_dwordx4 v[192:195], v170, s[98:99] offset:256 sc1
	global_load_dwordx4 v[224:227], v170, s[100:101] offset:256 sc1
	s_add_u32 s98, s98, 0x8000
	s_addc_u32 s99, s99, 0
	s_add_u32 s100, s100, 0x8000
	s_addc_u32 s101, s101, 0
	global_load_dwordx4 v[196:199], v170, s[98:99] sc1
	global_load_dwordx4 v[228:231], v170, s[100:101] sc1
	global_load_dwordx4 v[200:203], v170, s[98:99] offset:256 sc1
	global_load_dwordx4 v[232:235], v170, s[100:101] offset:256 sc1
	s_sub_u32 s98, s98, 0x18000
	s_subb_u32 s99, s99, 0
	s_sub_u32 s100, s100, 0x18000
	s_subb_u32 s101, s101, 0
	s_waitcnt vmcnt(14)
	v_lshlrev_b32_e32 v236, 16, v172
	v_lshlrev_b32_e32 v240, 16, v204
	v_and_b32_e32 v172, 0xffff0000, v172
	v_and_b32_e32 v204, 0xffff0000, v204
	v_lshlrev_b32_e32 v237, 16, v173
	v_lshlrev_b32_e32 v241, 16, v205
	v_and_b32_e32 v173, 0xffff0000, v173
	v_and_b32_e32 v205, 0xffff0000, v205
	v_lshlrev_b32_e32 v238, 16, v174
	v_lshlrev_b32_e32 v242, 16, v206
	v_and_b32_e32 v174, 0xffff0000, v174
	v_and_b32_e32 v206, 0xffff0000, v206
	v_lshlrev_b32_e32 v239, 16, v175
	v_lshlrev_b32_e32 v243, 16, v207
	v_and_b32_e32 v175, 0xffff0000, v175
	v_and_b32_e32 v207, 0xffff0000, v207
	v_fmac_f32_e32 v236, v124, v240
	v_fmac_f32_e32 v172, v125, v204
	v_fmac_f32_e32 v237, v126, v241
	v_fmac_f32_e32 v173, v127, v205
	v_fmac_f32_e32 v238, v120, v242
	v_fmac_f32_e32 v174, v121, v206
	v_fmac_f32_e32 v239, v122, v243
	v_fmac_f32_e32 v175, v123, v207
	v_cvt_pk_bf16_f32 v172, v236, v172
	v_cvt_pk_bf16_f32 v173, v237, v173
	v_cvt_pk_bf16_f32 v174, v238, v174
	v_cvt_pk_bf16_f32 v175, v239, v175
	global_store_dwordx4 v170, v[172:175], s[98:99]
	global_load_dwordx4 v[204:207], v171, s[100:101] sc1
	global_load_dwordx4 v[172:175], v171, s[98:99] sc1
	s_waitcnt vmcnt(15)
	v_lshlrev_b32_e32 v236, 16, v176
	v_lshlrev_b32_e32 v240, 16, v208
	v_and_b32_e32 v176, 0xffff0000, v176
	v_and_b32_e32 v208, 0xffff0000, v208
	v_lshlrev_b32_e32 v237, 16, v177
	v_lshlrev_b32_e32 v241, 16, v209
	v_and_b32_e32 v177, 0xffff0000, v177
	v_and_b32_e32 v209, 0xffff0000, v209
	v_lshlrev_b32_e32 v238, 16, v178
	v_lshlrev_b32_e32 v242, 16, v210
	v_and_b32_e32 v178, 0xffff0000, v178
	v_and_b32_e32 v210, 0xffff0000, v210
	v_lshlrev_b32_e32 v239, 16, v179
	v_lshlrev_b32_e32 v243, 16, v211
	v_and_b32_e32 v179, 0xffff0000, v179
	v_and_b32_e32 v211, 0xffff0000, v211
	v_fmac_f32_e32 v236, v116, v240
	v_fmac_f32_e32 v176, v117, v208
	v_fmac_f32_e32 v237, v118, v241
	v_fmac_f32_e32 v177, v119, v209
	v_fmac_f32_e32 v238, v112, v242
	v_fmac_f32_e32 v178, v113, v210
	v_fmac_f32_e32 v239, v114, v243
	v_fmac_f32_e32 v179, v115, v211
	v_cvt_pk_bf16_f32 v176, v236, v176
	v_cvt_pk_bf16_f32 v177, v237, v177
	v_cvt_pk_bf16_f32 v178, v238, v178
	v_cvt_pk_bf16_f32 v179, v239, v179
	global_store_dwordx4 v170, v[176:179], s[98:99] offset:256
	global_load_dwordx4 v[208:211], v171, s[100:101] offset:256 sc1
	global_load_dwordx4 v[176:179], v171, s[98:99] offset:256 sc1
	s_add_u32 s98, s98, 0x8000
	s_addc_u32 s99, s99, 0
	s_add_u32 s100, s100, 0x8000
	s_addc_u32 s101, s101, 0
	s_waitcnt vmcnt(16)
	v_lshlrev_b32_e32 v236, 16, v180
	v_lshlrev_b32_e32 v240, 16, v212
	v_and_b32_e32 v180, 0xffff0000, v180
	v_and_b32_e32 v212, 0xffff0000, v212
	v_lshlrev_b32_e32 v237, 16, v181
	v_lshlrev_b32_e32 v241, 16, v213
	v_and_b32_e32 v181, 0xffff0000, v181
	v_and_b32_e32 v213, 0xffff0000, v213
	v_lshlrev_b32_e32 v238, 16, v182
	v_lshlrev_b32_e32 v242, 16, v214
	v_and_b32_e32 v182, 0xffff0000, v182
	v_and_b32_e32 v214, 0xffff0000, v214
	v_lshlrev_b32_e32 v239, 16, v183
	v_lshlrev_b32_e32 v243, 16, v215
	v_and_b32_e32 v183, 0xffff0000, v183
	v_and_b32_e32 v215, 0xffff0000, v215
	v_fmac_f32_e32 v236, v108, v240
	v_fmac_f32_e32 v180, v109, v212
	v_fmac_f32_e32 v237, v110, v241
	v_fmac_f32_e32 v181, v111, v213
	v_fmac_f32_e32 v238, v104, v242
	v_fmac_f32_e32 v182, v105, v214
	v_fmac_f32_e32 v239, v106, v243
	v_fmac_f32_e32 v183, v107, v215
	v_cvt_pk_bf16_f32 v180, v236, v180
	v_cvt_pk_bf16_f32 v181, v237, v181
	v_cvt_pk_bf16_f32 v182, v238, v182
	v_cvt_pk_bf16_f32 v183, v239, v183
	global_store_dwordx4 v170, v[180:183], s[98:99]
	global_load_dwordx4 v[212:215], v171, s[100:101] sc1
	global_load_dwordx4 v[180:183], v171, s[98:99] sc1
	s_waitcnt vmcnt(17)
; DI unsigned pk2(float lo, float hi) { f32x2_t v = {lo, hi}; bf16x2_t b = __builtin_convertvector(v, bf16x2_t); return __builtin_bit_cast(unsigned, b); }
; DI float bf_lo(unsigned w) { return __uint_as_float(w << 16); }
; DI float bf_hi(unsigned w) { return __uint_as_float(w & 0xffff0000u); }
;     DI void operator()(AccRef acc, const Unit& u, int wr, int wc, int fr, int fq) const {
;     ...
;                     const u32x4 a = ld16_l2(M1 + off); u32x4 w;
;                     if (MODE == 0) {
;                         w.x = pk2(bf_lo(a.x) * v0[0], bf_hi(a.x) * v0[1]); w.y = pk2(bf_lo(a.y) * v0[2], bf_hi(a.y) * v0[3]);
;                         w.z = pk2(bf_lo(a.z) * v1[0], bf_hi(a.z) * v1[1]); w.w = pk2(bf_lo(a.w) * v1[2], bf_hi(a.w) * v1[3]);
;                     } else {
;                         const u32x4 b = ld16_l2(M2 + off);
;                         w.x = pk2(bf_lo(a.x) + bf_lo(b.x) * v0[0], bf_hi(a.x) + bf_hi(b.x) * v0[1]); w.y = pk2(bf_lo(a.y) + bf_lo(b.y) * v0[2], bf_hi(a.y) + bf_hi(b.y) * v0[3]);
;                         w.z = pk2(bf_lo(a.z) + bf_lo(b.z) * v1[0], bf_hi(a.z) + bf_hi(b.z) * v1[1]); w.w = pk2(bf_lo(a.w) + bf_lo(b.w) * v1[2], bf_hi(a.w) + bf_hi(b.w) * v1[3]);
;                     }
;                     *(u32x4*)(M1 + off) = w;
	v_lshlrev_b32_e32 v236, 16, v184
	v_lshlrev_b32_e32 v240, 16, v216
	v_and_b32_e32 v184, 0xffff0000, v184
	v_and_b32_e32 v216, 0xffff0000, v216
	v_lshlrev_b32_e32 v237, 16, v185
	v_lshlrev_b32_e32 v241, 16, v217
	v_and_b32_e32 v185, 0xffff0000, v185
	v_and_b32_e32 v217, 0xffff0000, v217
	v_lshlrev_b32_e32 v238, 16, v186
	v_lshlrev_b32_e32 v242, 16, v218
	v_and_b32_e32 v186, 0xffff0000, v186
	v_and_b32_e32 v218, 0xffff0000, v218
	v_lshlrev_b32_e32 v239, 16, v187
	v_lshlrev_b32_e32 v243, 16, v219
	v_and_b32_e32 v187, 0xffff0000, v187
	v_and_b32_e32 v219, 0xffff0000, v219
	v_fmac_f32_e32 v236, v100, v240
	v_fmac_f32_e32 v184, v101, v216
	v_fmac_f32_e32 v237, v102, v241
	v_fmac_f32_e32 v185, v103, v217
	v_fmac_f32_e32 v238, v96, v242
	v_fmac_f32_e32 v186, v97, v218
	v_fmac_f32_e32 v239, v98, v243
	v_fmac_f32_e32 v187, v99, v219
	v_cvt_pk_bf16_f32 v184, v236, v184
	v_cvt_pk_bf16_f32 v185, v237, v185
	v_cvt_pk_bf16_f32 v186, v238, v186
	v_cvt_pk_bf16_f32 v187, v239, v187
	global_store_dwordx4 v170, v[184:187], s[98:99] offset:256
	global_load_dwordx4 v[216:219], v171, s[100:101] offset:256 sc1
	global_load_dwordx4 v[184:187], v171, s[98:99] offset:256 sc1
	s_add_u32 s98, s98, 0x8000
	s_addc_u32 s99, s99, 0
	s_add_u32 s100, s100, 0x8000
	s_addc_u32 s101, s101, 0
	s_waitcnt vmcnt(18)
	v_lshlrev_b32_e32 v236, 16, v188
	v_lshlrev_b32_e32 v240, 16, v220
	v_and_b32_e32 v188, 0xffff0000, v188
	v_and_b32_e32 v220, 0xffff0000, v220
	v_lshlrev_b32_e32 v237, 16, v189
	v_lshlrev_b32_e32 v241, 16, v221
	v_and_b32_e32 v189, 0xffff0000, v189
	v_and_b32_e32 v221, 0xffff0000, v221
	v_lshlrev_b32_e32 v238, 16, v190
	v_lshlrev_b32_e32 v242, 16, v222
	v_and_b32_e32 v190, 0xffff0000, v190
	v_and_b32_e32 v222, 0xffff0000, v222
	v_lshlrev_b32_e32 v239, 16, v191
	v_lshlrev_b32_e32 v243, 16, v223
	v_and_b32_e32 v191, 0xffff0000, v191
	v_and_b32_e32 v223, 0xffff0000, v223
	v_fmac_f32_e32 v236, v92, v240
	v_fmac_f32_e32 v188, v93, v220
	v_fmac_f32_e32 v237, v94, v241
	v_fmac_f32_e32 v189, v95, v221
	v_fmac_f32_e32 v238, v88, v242
	v_fmac_f32_e32 v190, v89, v222
	v_fmac_f32_e32 v239, v90, v243
	v_fmac_f32_e32 v191, v91, v223
	v_cvt_pk_bf16_f32 v188, v236, v188
	v_cvt_pk_bf16_f32 v189, v237, v189
	v_cvt_pk_bf16_f32 v190, v238, v190
	v_cvt_pk_bf16_f32 v191, v239, v191
	global_store_dwordx4 v170, v[188:191], s[98:99]
	global_load_dwordx4 v[220:223], v171, s[100:101] sc1
	global_load_dwordx4 v[188:191], v171, s[98:99] sc1
	s_waitcnt vmcnt(19)
	v_lshlrev_b32_e32 v236, 16, v192
	v_lshlrev_b32_e32 v240, 16, v224
	v_and_b32_e32 v192, 0xffff0000, v192
	v_and_b32_e32 v224, 0xffff0000, v224
	v_lshlrev_b32_e32 v237, 16, v193
	v_lshlrev_b32_e32 v241, 16, v225
	v_and_b32_e32 v193, 0xffff0000, v193
	v_and_b32_e32 v225, 0xffff0000, v225
	v_lshlrev_b32_e32 v238, 16, v194
	v_lshlrev_b32_e32 v242, 16, v226
	v_and_b32_e32 v194, 0xffff0000, v194
	v_and_b32_e32 v226, 0xffff0000, v226
	v_lshlrev_b32_e32 v239, 16, v195
	v_lshlrev_b32_e32 v243, 16, v227
	v_and_b32_e32 v195, 0xffff0000, v195
	v_and_b32_e32 v227, 0xffff0000, v227
	v_fmac_f32_e32 v236, v84, v240
	v_fmac_f32_e32 v192, v85, v224
	v_fmac_f32_e32 v237, v86, v241
	v_fmac_f32_e32 v193, v87, v225
	v_fmac_f32_e32 v238, v80, v242
	v_fmac_f32_e32 v194, v81, v226
	v_fmac_f32_e32 v239, v82, v243
	v_fmac_f32_e32 v195, v83, v227
	v_cvt_pk_bf16_f32 v192, v236, v192
	v_cvt_pk_bf16_f32 v193, v237, v193
	v_cvt_pk_bf16_f32 v194, v238, v194
	v_cvt_pk_bf16_f32 v195, v239, v195
	global_store_dwordx4 v170, v[192:195], s[98:99] offset:256
	global_load_dwordx4 v[224:227], v171, s[100:101] offset:256 sc1
	global_load_dwordx4 v[192:195], v171, s[98:99] offset:256 sc1
	s_add_u32 s98, s98, 0x8000
	s_addc_u32 s99, s99, 0
	s_add_u32 s100, s100, 0x8000
	s_addc_u32 s101, s101, 0
	s_waitcnt vmcnt(20)
	v_lshlrev_b32_e32 v236, 16, v196
	v_lshlrev_b32_e32 v240, 16, v228
	v_and_b32_e32 v196, 0xffff0000, v196
	v_and_b32_e32 v228, 0xffff0000, v228
	v_lshlrev_b32_e32 v237, 16, v197
	v_lshlrev_b32_e32 v241, 16, v229
	v_and_b32_e32 v197, 0xffff0000, v197
	v_and_b32_e32 v229, 0xffff0000, v229
	v_lshlrev_b32_e32 v238, 16, v198
	v_lshlrev_b32_e32 v242, 16, v230
	v_and_b32_e32 v198, 0xffff0000, v198
	v_and_b32_e32 v230, 0xffff0000, v230
	v_lshlrev_b32_e32 v239, 16, v199
	v_lshlrev_b32_e32 v243, 16, v231
	v_and_b32_e32 v199, 0xffff0000, v199
	v_and_b32_e32 v231, 0xffff0000, v231
	v_fmac_f32_e32 v236, v76, v240
	v_fmac_f32_e32 v196, v77, v228
	v_fmac_f32_e32 v237, v78, v241
	v_fmac_f32_e32 v197, v79, v229
	v_fmac_f32_e32 v238, v72, v242
	v_fmac_f32_e32 v198, v73, v230
	v_fmac_f32_e32 v239, v74, v243
	v_fmac_f32_e32 v199, v75, v231
	v_cvt_pk_bf16_f32 v196, v236, v196
	v_cvt_pk_bf16_f32 v197, v237, v197
	v_cvt_pk_bf16_f32 v198, v238, v198
	v_cvt_pk_bf16_f32 v199, v239, v199
	global_store_dwordx4 v170, v[196:199], s[98:99]
	global_load_dwordx4 v[228:231], v171, s[100:101] sc1
	global_load_dwordx4 v[196:199], v171, s[98:99] sc1
	s_waitcnt vmcnt(21)
	v_lshlrev_b32_e32 v236, 16, v200
	v_lshlrev_b32_e32 v240, 16, v232
	v_and_b32_e32 v200, 0xffff0000, v200
	v_and_b32_e32 v232, 0xffff0000, v232
	v_lshlrev_b32_e32 v237, 16, v201
	v_lshlrev_b32_e32 v241, 16, v233
	v_and_b32_e32 v201, 0xffff0000, v201
	v_and_b32_e32 v233, 0xffff0000, v233
	v_lshlrev_b32_e32 v238, 16, v202
	v_lshlrev_b32_e32 v242, 16, v234
	v_and_b32_e32 v202, 0xffff0000, v202
	v_and_b32_e32 v234, 0xffff0000, v234
	v_lshlrev_b32_e32 v239, 16, v203
	v_lshlrev_b32_e32 v243, 16, v235
	v_and_b32_e32 v203, 0xffff0000, v203
	v_and_b32_e32 v235, 0xffff0000, v235
	v_fmac_f32_e32 v236, v68, v240
	v_fmac_f32_e32 v200, v69, v232
	v_fmac_f32_e32 v237, v70, v241
	v_fmac_f32_e32 v201, v71, v233
	v_fmac_f32_e32 v238, v64, v242
	v_fmac_f32_e32 v202, v65, v234
	v_fmac_f32_e32 v239, v66, v243
	v_fmac_f32_e32 v203, v67, v235
	v_cvt_pk_bf16_f32 v200, v236, v200
	v_cvt_pk_bf16_f32 v201, v237, v201
	v_cvt_pk_bf16_f32 v202, v238, v202
	v_cvt_pk_bf16_f32 v203, v239, v203
	global_store_dwordx4 v170, v[200:203], s[98:99] offset:256
	global_load_dwordx4 v[232:235], v171, s[100:101] offset:256 sc1
	global_load_dwordx4 v[200:203], v171, s[98:99] offset:256 sc1
	s_sub_u32 s98, s98, 0x18000
	s_subb_u32 s99, s99, 0
	s_sub_u32 s100, s100, 0x18000
	s_subb_u32 s101, s101, 0
	s_waitcnt vmcnt(21)
; DI unsigned pk2(float lo, float hi) { f32x2_t v = {lo, hi}; bf16x2_t b = __builtin_convertvector(v, bf16x2_t); return __builtin_bit_cast(unsigned, b); }
; DI float bf_lo(unsigned w) { return __uint_as_float(w << 16); }
; DI float bf_hi(unsigned w) { return __uint_as_float(w & 0xffff0000u); }
;     DI void operator()(AccRef acc, const Unit& u, int wr, int wc, int fr, int fq) const {
;     ...
;                     const u32x4 a = ld16_l2(M1 + off); u32x4 w;
;                     if (MODE == 0) {
;                         w.x = pk2(bf_lo(a.x) * v0[0], bf_hi(a.x) * v0[1]); w.y = pk2(bf_lo(a.y) * v0[2], bf_hi(a.y) * v0[3]);
;                         w.z = pk2(bf_lo(a.z) * v1[0], bf_hi(a.z) * v1[1]); w.w = pk2(bf_lo(a.w) * v1[2], bf_hi(a.w) * v1[3]);
;                     } else {
;                         const u32x4 b = ld16_l2(M2 + off);
;                         w.x = pk2(bf_lo(a.x) + bf_lo(b.x) * v0[0], bf_hi(a.x) + bf_hi(b.x) * v0[1]); w.y = pk2(bf_lo(a.y) + bf_lo(b.y) * v0[2], bf_hi(a.y) + bf_hi(b.y) * v0[3]);
;                         w.z = pk2(bf_lo(a.z) + bf_lo(b.z) * v1[0], bf_hi(a.z) + bf_hi(b.z) * v1[1]); w.w = pk2(bf_lo(a.w) + bf_lo(b.w) * v1[2], bf_hi(a.w) + bf_hi(b.w) * v1[3]);
;                     }
;                     *(u32x4*)(M1 + off) = w;
	v_lshlrev_b32_e32 v236, 16, v172
	v_lshlrev_b32_e32 v240, 16, v204
	v_and_b32_e32 v172, 0xffff0000, v172
	v_and_b32_e32 v204, 0xffff0000, v204
	v_lshlrev_b32_e32 v237, 16, v173
	v_lshlrev_b32_e32 v241, 16, v205
	v_and_b32_e32 v173, 0xffff0000, v173
	v_and_b32_e32 v205, 0xffff0000, v205
	v_lshlrev_b32_e32 v238, 16, v174
	v_lshlrev_b32_e32 v242, 16, v206
	v_and_b32_e32 v174, 0xffff0000, v174
	v_and_b32_e32 v206, 0xffff0000, v206
	v_lshlrev_b32_e32 v239, 16, v175
	v_lshlrev_b32_e32 v243, 16, v207
	v_and_b32_e32 v175, 0xffff0000, v175
	v_and_b32_e32 v207, 0xffff0000, v207
	v_fmac_f32_e32 v236, v60, v240
	v_fmac_f32_e32 v172, v61, v204
	v_fmac_f32_e32 v237, v62, v241
	v_fmac_f32_e32 v173, v63, v205
	v_fmac_f32_e32 v238, v56, v242
	v_fmac_f32_e32 v174, v57, v206
	v_fmac_f32_e32 v239, v58, v243
	v_fmac_f32_e32 v175, v59, v207
	v_cvt_pk_bf16_f32 v172, v236, v172
	v_cvt_pk_bf16_f32 v173, v237, v173
	v_cvt_pk_bf16_f32 v174, v238, v174
	v_cvt_pk_bf16_f32 v175, v239, v175
	global_store_dwordx4 v171, v[172:175], s[98:99]
	s_waitcnt vmcnt(19)
	v_lshlrev_b32_e32 v236, 16, v176
	v_lshlrev_b32_e32 v240, 16, v208
	v_and_b32_e32 v176, 0xffff0000, v176
	v_and_b32_e32 v208, 0xffff0000, v208
	v_lshlrev_b32_e32 v237, 16, v177
	v_lshlrev_b32_e32 v241, 16, v209
	v_and_b32_e32 v177, 0xffff0000, v177
	v_and_b32_e32 v209, 0xffff0000, v209
	v_lshlrev_b32_e32 v238, 16, v178
	v_lshlrev_b32_e32 v242, 16, v210
	v_and_b32_e32 v178, 0xffff0000, v178
	v_and_b32_e32 v210, 0xffff0000, v210
	v_lshlrev_b32_e32 v239, 16, v179
	v_lshlrev_b32_e32 v243, 16, v211
	v_and_b32_e32 v179, 0xffff0000, v179
	v_and_b32_e32 v211, 0xffff0000, v211
	v_fmac_f32_e32 v236, v52, v240
	v_fmac_f32_e32 v176, v53, v208
	v_fmac_f32_e32 v237, v54, v241
	v_fmac_f32_e32 v177, v55, v209
	v_fmac_f32_e32 v238, v48, v242
	v_fmac_f32_e32 v178, v49, v210
	v_fmac_f32_e32 v239, v50, v243
	v_fmac_f32_e32 v179, v51, v211
	v_cvt_pk_bf16_f32 v176, v236, v176
	v_cvt_pk_bf16_f32 v177, v237, v177
	v_cvt_pk_bf16_f32 v178, v238, v178
	v_cvt_pk_bf16_f32 v179, v239, v179
	global_store_dwordx4 v171, v[176:179], s[98:99] offset:256
	s_add_u32 s98, s98, 0x8000
	s_addc_u32 s99, s99, 0
	s_add_u32 s100, s100, 0x8000
	s_addc_u32 s101, s101, 0
	s_waitcnt vmcnt(17)
	v_lshlrev_b32_e32 v236, 16, v180
	v_lshlrev_b32_e32 v240, 16, v212
	v_and_b32_e32 v180, 0xffff0000, v180
	v_and_b32_e32 v212, 0xffff0000, v212
	v_lshlrev_b32_e32 v237, 16, v181
	v_lshlrev_b32_e32 v241, 16, v213
	v_and_b32_e32 v181, 0xffff0000, v181
	v_and_b32_e32 v213, 0xffff0000, v213
	v_lshlrev_b32_e32 v238, 16, v182
	v_lshlrev_b32_e32 v242, 16, v214
	v_and_b32_e32 v182, 0xffff0000, v182
	v_and_b32_e32 v214, 0xffff0000, v214
	v_lshlrev_b32_e32 v239, 16, v183
	v_lshlrev_b32_e32 v243, 16, v215
	v_and_b32_e32 v183, 0xffff0000, v183
	v_and_b32_e32 v215, 0xffff0000, v215
	v_fmac_f32_e32 v236, v44, v240
	v_fmac_f32_e32 v180, v45, v212
	v_fmac_f32_e32 v237, v46, v241
	v_fmac_f32_e32 v181, v47, v213
	v_fmac_f32_e32 v238, v40, v242
	v_fmac_f32_e32 v182, v41, v214
	v_fmac_f32_e32 v239, v42, v243
	v_fmac_f32_e32 v183, v43, v215
	v_cvt_pk_bf16_f32 v180, v236, v180
	v_cvt_pk_bf16_f32 v181, v237, v181
	v_cvt_pk_bf16_f32 v182, v238, v182
	v_cvt_pk_bf16_f32 v183, v239, v183
	global_store_dwordx4 v171, v[180:183], s[98:99]
	s_waitcnt vmcnt(15)
	v_lshlrev_b32_e32 v236, 16, v184
	v_lshlrev_b32_e32 v240, 16, v216
	v_and_b32_e32 v184, 0xffff0000, v184
	v_and_b32_e32 v216, 0xffff0000, v216
	v_lshlrev_b32_e32 v237, 16, v185
	v_lshlrev_b32_e32 v241, 16, v217
	v_and_b32_e32 v185, 0xffff0000, v185
	v_and_b32_e32 v217, 0xffff0000, v217
	v_lshlrev_b32_e32 v238, 16, v186
	v_lshlrev_b32_e32 v242, 16, v218
	v_and_b32_e32 v186, 0xffff0000, v186
	v_and_b32_e32 v218, 0xffff0000, v218
	v_lshlrev_b32_e32 v239, 16, v187
	v_lshlrev_b32_e32 v243, 16, v219
	v_and_b32_e32 v187, 0xffff0000, v187
	v_and_b32_e32 v219, 0xffff0000, v219
	v_fmac_f32_e32 v236, v36, v240
	v_fmac_f32_e32 v184, v37, v216
	v_fmac_f32_e32 v237, v38, v241
	v_fmac_f32_e32 v185, v39, v217
	v_fmac_f32_e32 v238, v32, v242
	v_fmac_f32_e32 v186, v33, v218
	v_fmac_f32_e32 v239, v34, v243
	v_fmac_f32_e32 v187, v35, v219
	v_cvt_pk_bf16_f32 v184, v236, v184
	v_cvt_pk_bf16_f32 v185, v237, v185
	v_cvt_pk_bf16_f32 v186, v238, v186
	v_cvt_pk_bf16_f32 v187, v239, v187
	global_store_dwordx4 v171, v[184:187], s[98:99] offset:256
	s_add_u32 s98, s98, 0x8000
	s_addc_u32 s99, s99, 0
	s_add_u32 s100, s100, 0x8000
	s_addc_u32 s101, s101, 0
	s_waitcnt vmcnt(13)
; DI unsigned pk2(float lo, float hi) { f32x2_t v = {lo, hi}; bf16x2_t b = __builtin_convertvector(v, bf16x2_t); return __builtin_bit_cast(unsigned, b); }
; DI float bf_lo(unsigned w) { return __uint_as_float(w << 16); }
; DI float bf_hi(unsigned w) { return __uint_as_float(w & 0xffff0000u); }
;     DI void operator()(AccRef acc, const Unit& u, int wr, int wc, int fr, int fq) const {
;     ...
;                     const u32x4 a = ld16_l2(M1 + off); u32x4 w;
;                     if (MODE == 0) {
;                         w.x = pk2(bf_lo(a.x) * v0[0], bf_hi(a.x) * v0[1]); w.y = pk2(bf_lo(a.y) * v0[2], bf_hi(a.y) * v0[3]);
;                         w.z = pk2(bf_lo(a.z) * v1[0], bf_hi(a.z) * v1[1]); w.w = pk2(bf_lo(a.w) * v1[2], bf_hi(a.w) * v1[3]);
;                     } else {
;                         const u32x4 b = ld16_l2(M2 + off);
;                         w.x = pk2(bf_lo(a.x) + bf_lo(b.x) * v0[0], bf_hi(a.x) + bf_hi(b.x) * v0[1]); w.y = pk2(bf_lo(a.y) + bf_lo(b.y) * v0[2], bf_hi(a.y) + bf_hi(b.y) * v0[3]);
;                         w.z = pk2(bf_lo(a.z) + bf_lo(b.z) * v1[0], bf_hi(a.z) + bf_hi(b.z) * v1[1]); w.w = pk2(bf_lo(a.w) + bf_lo(b.w) * v1[2], bf_hi(a.w) + bf_hi(b.w) * v1[3]);
;                     }
;                     *(u32x4*)(M1 + off) = w;
	v_lshlrev_b32_e32 v236, 16, v188
	v_lshlrev_b32_e32 v240, 16, v220
	v_and_b32_e32 v188, 0xffff0000, v188
	v_and_b32_e32 v220, 0xffff0000, v220
	v_lshlrev_b32_e32 v237, 16, v189
	v_lshlrev_b32_e32 v241, 16, v221
	v_and_b32_e32 v189, 0xffff0000, v189
	v_and_b32_e32 v221, 0xffff0000, v221
	v_lshlrev_b32_e32 v238, 16, v190
	v_lshlrev_b32_e32 v242, 16, v222
	v_and_b32_e32 v190, 0xffff0000, v190
	v_and_b32_e32 v222, 0xffff0000, v222
	v_lshlrev_b32_e32 v239, 16, v191
	v_lshlrev_b32_e32 v243, 16, v223
	v_and_b32_e32 v191, 0xffff0000, v191
	v_and_b32_e32 v223, 0xffff0000, v223
	v_fmac_f32_e32 v236, v28, v240
	v_fmac_f32_e32 v188, v29, v220
	v_fmac_f32_e32 v237, v30, v241
	v_fmac_f32_e32 v189, v31, v221
	v_fmac_f32_e32 v238, v24, v242
	v_fmac_f32_e32 v190, v25, v222
	v_fmac_f32_e32 v239, v26, v243
	v_fmac_f32_e32 v191, v27, v223
	v_cvt_pk_bf16_f32 v188, v236, v188
	v_cvt_pk_bf16_f32 v189, v237, v189
	v_cvt_pk_bf16_f32 v190, v238, v190
	v_cvt_pk_bf16_f32 v191, v239, v191
	global_store_dwordx4 v171, v[188:191], s[98:99]
	s_waitcnt vmcnt(11)
	v_lshlrev_b32_e32 v236, 16, v192
	v_lshlrev_b32_e32 v240, 16, v224
	v_and_b32_e32 v192, 0xffff0000, v192
	v_and_b32_e32 v224, 0xffff0000, v224
	v_lshlrev_b32_e32 v237, 16, v193
	v_lshlrev_b32_e32 v241, 16, v225
	v_and_b32_e32 v193, 0xffff0000, v193
	v_and_b32_e32 v225, 0xffff0000, v225
	v_lshlrev_b32_e32 v238, 16, v194
	v_lshlrev_b32_e32 v242, 16, v226
	v_and_b32_e32 v194, 0xffff0000, v194
	v_and_b32_e32 v226, 0xffff0000, v226
	v_lshlrev_b32_e32 v239, 16, v195
	v_lshlrev_b32_e32 v243, 16, v227
	v_and_b32_e32 v195, 0xffff0000, v195
	v_and_b32_e32 v227, 0xffff0000, v227
	v_fmac_f32_e32 v236, v20, v240
	v_fmac_f32_e32 v192, v21, v224
	v_fmac_f32_e32 v237, v22, v241
	v_fmac_f32_e32 v193, v23, v225
	v_fmac_f32_e32 v238, v16, v242
	v_fmac_f32_e32 v194, v17, v226
	v_fmac_f32_e32 v239, v18, v243
	v_fmac_f32_e32 v195, v19, v227
	v_cvt_pk_bf16_f32 v192, v236, v192
	v_cvt_pk_bf16_f32 v193, v237, v193
	v_cvt_pk_bf16_f32 v194, v238, v194
	v_cvt_pk_bf16_f32 v195, v239, v195
	global_store_dwordx4 v171, v[192:195], s[98:99] offset:256
	s_add_u32 s98, s98, 0x8000
	s_addc_u32 s99, s99, 0
	s_add_u32 s100, s100, 0x8000
	s_addc_u32 s101, s101, 0
	s_waitcnt vmcnt(9)
	v_lshlrev_b32_e32 v236, 16, v196
	v_lshlrev_b32_e32 v240, 16, v228
	v_and_b32_e32 v196, 0xffff0000, v196
	v_and_b32_e32 v228, 0xffff0000, v228
	v_lshlrev_b32_e32 v237, 16, v197
	v_lshlrev_b32_e32 v241, 16, v229
	v_and_b32_e32 v197, 0xffff0000, v197
	v_and_b32_e32 v229, 0xffff0000, v229
	v_lshlrev_b32_e32 v238, 16, v198
	v_lshlrev_b32_e32 v242, 16, v230
	v_and_b32_e32 v198, 0xffff0000, v198
	v_and_b32_e32 v230, 0xffff0000, v230
	v_lshlrev_b32_e32 v239, 16, v199
	v_lshlrev_b32_e32 v243, 16, v231
	v_and_b32_e32 v199, 0xffff0000, v199
	v_and_b32_e32 v231, 0xffff0000, v231
	v_fmac_f32_e32 v236, v12, v240
	v_fmac_f32_e32 v196, v13, v228
	v_fmac_f32_e32 v237, v14, v241
	v_fmac_f32_e32 v197, v15, v229
	v_fmac_f32_e32 v238, v8, v242
	v_fmac_f32_e32 v198, v9, v230
	v_fmac_f32_e32 v239, v10, v243
	v_fmac_f32_e32 v199, v11, v231
	v_cvt_pk_bf16_f32 v196, v236, v196
	v_cvt_pk_bf16_f32 v197, v237, v197
	v_cvt_pk_bf16_f32 v198, v238, v198
	v_cvt_pk_bf16_f32 v199, v239, v199
	global_store_dwordx4 v171, v[196:199], s[98:99]
	s_waitcnt vmcnt(7)
	v_lshlrev_b32_e32 v236, 16, v200
	v_lshlrev_b32_e32 v240, 16, v232
	v_and_b32_e32 v200, 0xffff0000, v200
	v_and_b32_e32 v232, 0xffff0000, v232
	v_lshlrev_b32_e32 v237, 16, v201
	v_lshlrev_b32_e32 v241, 16, v233
	v_and_b32_e32 v201, 0xffff0000, v201
	v_and_b32_e32 v233, 0xffff0000, v233
	v_lshlrev_b32_e32 v238, 16, v202
	v_lshlrev_b32_e32 v242, 16, v234
	v_and_b32_e32 v202, 0xffff0000, v202
	v_and_b32_e32 v234, 0xffff0000, v234
	v_lshlrev_b32_e32 v239, 16, v203
	v_lshlrev_b32_e32 v243, 16, v235
	v_and_b32_e32 v203, 0xffff0000, v203
	v_and_b32_e32 v235, 0xffff0000, v235
	v_fmac_f32_e32 v236, v4, v240
	v_fmac_f32_e32 v200, v5, v232
	v_fmac_f32_e32 v237, v6, v241
	v_fmac_f32_e32 v201, v7, v233
	v_fmac_f32_e32 v238, v0, v242
	v_fmac_f32_e32 v202, v1, v234
	v_fmac_f32_e32 v239, v2, v243
	v_fmac_f32_e32 v203, v3, v235
	v_cvt_pk_bf16_f32 v200, v236, v200
	v_cvt_pk_bf16_f32 v201, v237, v201
	v_cvt_pk_bf16_f32 v202, v238, v202
	v_cvt_pk_bf16_f32 v203, v239, v203
	global_store_dwordx4 v171, v[200:203], s[98:99] offset:256
	s_mov_b32 s21, 0x40000
	s_mov_b64 s[30:31], 0x48000
	s_andn2_b64 vcc, exec, s[2:3]
	s_mov_b64 s[2:3], -1
	s_cbranch_vccnz .LBB0_1311
	s_andn2_b64 vcc, exec, s[0:1]
	s_cbranch_vccnz .LBB0_1310
	s_barrier
	s_branch .LBB0_1310

; DI unsigned pk2(float lo, float hi) { f32x2_t v = {lo, hi}; bf16x2_t b = __builtin_convertvector(v, bf16x2_t); return __builtin_bit_cast(unsigned, b); }
; DI float bf_lo(unsigned w) { return __uint_as_float(w << 16); }
; DI float bf_hi(unsigned w) { return __uint_as_float(w & 0xffff0000u); }
;     DI f32x4 base4(int row, int col) const {
;         if (FIRST) return *(const f32x4*)((row < TOKP ? xp + (size_t)row * DM : xs + (size_t)(row - TOKP) * DM) + col);
;         const u32x2 w = *(const u32x2*)(XB + (size_t)row * DM + col); return (f32x4){bf_lo(w.x), bf_hi(w.x), bf_lo(w.y), bf_hi(w.y)};
;     }
;     DI void operator()(AccRef acc, const Unit& u, int wr, int wc, int fr, int fq) const {
;         const int row0 = rowoff + u.pm * BM + wr * 64 + fr, col0 = u.pn * BM + wc * 32 + 4 * fq;
; #pragma unroll
;         for (int ai = 0; ai < 2; ++ai)
; #pragma unroll
;             for (int m = 0; m < 4; ++m) {
;                 const int row = row0 + ai * HALF + m * 16; float ss = 0.f;
; #pragma unroll
;                 for (int bj = 0; bj < 2; ++bj)
; #pragma unroll
;                     for (int n = 0; n < 2; ++n) {
;                         const int col = col0 + bj * HALF + n * 16;
;                         const f32x4 x = base4(row, col) + acc[ai][bj][m][n];
;                         ss += (x[0] * x[0] + x[1] * x[1]) + (x[2] * x[2] + x[3] * x[3]);
;                         if (FIRST && !dry) { u32x2 w; w.x = pk2(x[0], x[1]); w.y = pk2(x[2], x[3]); *(u32x2*)(XB + (size_t)row * DM + col) = w; }
;                     }
;                 ss += __shfl_xor(ss, 16); ss += __shfl_xor(ss, 32);
;                 if (fq == 0 && !dry) unsafeAtomicAdd(SS + row, ss);
.LBB0_1403:
	v_lshlrev_b32_e32 v140, 12, v144
	v_lshl_add_u32 v140, v146, 2, v140
	v_lshlrev_b32_e32 v141, 11, v144
	v_lshl_add_u32 v141, v146, 1, v141
	v_lshlrev_b32_e32 v142, 2, v144
	s_lshl_b32 s100, s20, 10
	v_add_u32_e32 v142, s100, v142
	v_xor_b32_e32 v143, 16, v152
	v_lshlrev_b32_e32 v143, 2, v143
	v_xor_b32_e32 v153, 32, v152
	v_lshlrev_b32_e32 v153, 2, v153
	s_cmp_lt_u32 s20, 64
	s_cselect_b32 s98, s64, s66
	s_cselect_b32 s99, s65, s67
	s_cselect_b32 s21, 0, 64
	s_sub_u32 s21, s20, s21
	s_lshl_b32 s21, s21, 20
	s_lshl_b32 s100, s22, 10
	s_add_u32 s21, s21, s100
	s_add_u32 s98, s98, s21
	s_addc_u32 s99, s99, 0
	s_lshl_b32 s21, s20, 19
	s_lshl_b32 s100, s22, 9
	s_add_u32 s21, s21, s100
	s_add_u32 s100, s92, s21
	s_addc_u32 s101, s93, 0
	global_load_dwordx4 v[154:157], v140, s[98:99]
	global_load_dwordx4 v[158:161], v140, s[98:99] offset:64
	global_load_dwordx4 v[162:165], v140, s[98:99] offset:512
	global_load_dwordx4 v[166:169], v140, s[98:99] offset:576
	s_add_u32 s98, s98, 0x10000
	s_addc_u32 s99, s99, 0
	global_load_dwordx4 v[170:173], v140, s[98:99]
	global_load_dwordx4 v[174:177], v140, s[98:99] offset:64
	global_load_dwordx4 v[178:181], v140, s[98:99] offset:512
	global_load_dwordx4 v[182:185], v140, s[98:99] offset:576
	s_add_u32 s98, s98, 0x10000
	s_addc_u32 s99, s99, 0
	global_load_dwordx4 v[186:189], v140, s[98:99]
	global_load_dwordx4 v[190:193], v140, s[98:99] offset:64
	global_load_dwordx4 v[194:197], v140, s[98:99] offset:512
	global_load_dwordx4 v[198:201], v140, s[98:99] offset:576
	s_add_u32 s98, s98, 0x10000
	s_addc_u32 s99, s99, 0
	global_load_dwordx4 v[202:205], v140, s[98:99]
	global_load_dwordx4 v[206:209], v140, s[98:99] offset:64
	global_load_dwordx4 v[210:213], v140, s[98:99] offset:512
	global_load_dwordx4 v[214:217], v140, s[98:99] offset:576
	s_add_u32 s98, s98, 0x10000
	s_addc_u32 s99, s99, 0
	s_add_u32 s98, s98, 0x40000
	s_addc_u32 s99, s99, 0
	s_waitcnt vmcnt(12)
	v_pk_add_f32 v[156:157], v[126:127], v[156:157]
	v_pk_add_f32 v[154:155], v[124:125], v[154:155]
	v_cvt_pk_bf16_f32 v125, v156, v157
	v_cvt_pk_bf16_f32 v124, v154, v155
	global_store_dwordx2 v141, v[124:125], s[100:101]
	v_mul_f32_e32 v218, v155, v155
	v_mul_f32_e32 v219, v157, v157
	v_fmac_f32_e32 v218, v154, v154
	v_fmac_f32_e32 v219, v156, v156
	v_add_f32_e32 v220, v218, v219
	v_pk_add_f32 v[160:161], v[122:123], v[160:161]
	v_pk_add_f32 v[158:159], v[120:121], v[158:159]
	v_cvt_pk_bf16_f32 v121, v160, v161
	v_cvt_pk_bf16_f32 v120, v158, v159
	global_store_dwordx2 v141, v[120:121], s[100:101] offset:32
	v_mul_f32_e32 v218, v159, v159
	v_mul_f32_e32 v219, v161, v161
	v_fmac_f32_e32 v218, v158, v158
	v_fmac_f32_e32 v219, v160, v160
	v_add_f32_e32 v218, v218, v219
	v_add_f32_e32 v220, v220, v218
	v_pk_add_f32 v[164:165], v[118:119], v[164:165]
	v_pk_add_f32 v[162:163], v[116:117], v[162:163]
	v_cvt_pk_bf16_f32 v117, v164, v165
	v_cvt_pk_bf16_f32 v116, v162, v163
	global_store_dwordx2 v141, v[116:117], s[100:101] offset:256
	v_mul_f32_e32 v218, v163, v163
	v_mul_f32_e32 v219, v165, v165
	v_fmac_f32_e32 v218, v162, v162
	v_fmac_f32_e32 v219, v164, v164
	v_add_f32_e32 v218, v218, v219
	v_add_f32_e32 v220, v220, v218
	v_pk_add_f32 v[168:169], v[114:115], v[168:169]
	v_pk_add_f32 v[166:167], v[112:113], v[166:167]
	v_cvt_pk_bf16_f32 v113, v168, v169
	v_cvt_pk_bf16_f32 v112, v166, v167
	global_store_dwordx2 v141, v[112:113], s[100:101] offset:288
	v_mul_f32_e32 v218, v167, v167
	v_mul_f32_e32 v219, v169, v169
	v_fmac_f32_e32 v218, v166, v166
	v_fmac_f32_e32 v219, v168, v168
	v_add_f32_e32 v218, v218, v219
	v_add_f32_e32 v220, v220, v218
	ds_bpermute_b32 v221, v143, v220
	s_waitcnt lgkmcnt(0)
	v_add_f32_e32 v220, v220, v221
	ds_bpermute_b32 v221, v153, v220
	s_waitcnt lgkmcnt(0)
	v_add_f32_e32 v220, v220, v221
	s_and_saveexec_b64 s[20:21], s[2:3]
	global_atomic_add_f32 v142, v220, s[46:47]
	s_or_b64 exec, exec, s[20:21]
	global_load_dwordx4 v[154:157], v140, s[98:99]
	global_load_dwordx4 v[158:161], v140, s[98:99] offset:64
	global_load_dwordx4 v[162:165], v140, s[98:99] offset:512
	global_load_dwordx4 v[166:169], v140, s[98:99] offset:576
	s_add_u32 s98, s98, 0x10000
	s_addc_u32 s99, s99, 0
	s_add_u32 s100, s100, 0x8000
	s_addc_u32 s101, s101, 0
	s_waitcnt vmcnt(17)
	v_pk_add_f32 v[172:173], v[110:111], v[172:173]
	v_pk_add_f32 v[170:171], v[108:109], v[170:171]
	v_cvt_pk_bf16_f32 v109, v172, v173
	v_cvt_pk_bf16_f32 v108, v170, v171
	global_store_dwordx2 v141, v[108:109], s[100:101]
	v_mul_f32_e32 v218, v171, v171
	v_mul_f32_e32 v219, v173, v173
	v_fmac_f32_e32 v218, v170, v170
	v_fmac_f32_e32 v219, v172, v172
	v_add_f32_e32 v220, v218, v219
	v_pk_add_f32 v[176:177], v[106:107], v[176:177]
	v_pk_add_f32 v[174:175], v[104:105], v[174:175]
	v_cvt_pk_bf16_f32 v105, v176, v177
	v_cvt_pk_bf16_f32 v104, v174, v175
	global_store_dwordx2 v141, v[104:105], s[100:101] offset:32
	v_mul_f32_e32 v218, v175, v175
	v_mul_f32_e32 v219, v177, v177
	v_fmac_f32_e32 v218, v174, v174
	v_fmac_f32_e32 v219, v176, v176
	v_add_f32_e32 v218, v218, v219
	v_add_f32_e32 v220, v220, v218
	v_pk_add_f32 v[180:181], v[102:103], v[180:181]
	v_pk_add_f32 v[178:179], v[100:101], v[178:179]
	v_cvt_pk_bf16_f32 v101, v180, v181
	v_cvt_pk_bf16_f32 v100, v178, v179
	global_store_dwordx2 v141, v[100:101], s[100:101] offset:256
	v_mul_f32_e32 v218, v179, v179
	v_mul_f32_e32 v219, v181, v181
	v_fmac_f32_e32 v218, v178, v178
	v_fmac_f32_e32 v219, v180, v180
	v_add_f32_e32 v218, v218, v219
	v_add_f32_e32 v220, v220, v218
	v_pk_add_f32 v[184:185], v[98:99], v[184:185]
	v_pk_add_f32 v[182:183], v[96:97], v[182:183]
	v_cvt_pk_bf16_f32 v97, v184, v185
	v_cvt_pk_bf16_f32 v96, v182, v183
	global_store_dwordx2 v141, v[96:97], s[100:101] offset:288
	v_mul_f32_e32 v218, v183, v183
	v_mul_f32_e32 v219, v185, v185
	v_fmac_f32_e32 v218, v182, v182
	v_fmac_f32_e32 v219, v184, v184
	v_add_f32_e32 v218, v218, v219
	v_add_f32_e32 v220, v220, v218
	ds_bpermute_b32 v221, v143, v220
	s_waitcnt lgkmcnt(0)
; DI unsigned pk2(float lo, float hi) { f32x2_t v = {lo, hi}; bf16x2_t b = __builtin_convertvector(v, bf16x2_t); return __builtin_bit_cast(unsigned, b); }
;     DI void operator()(AccRef acc, const Unit& u, int wr, int wc, int fr, int fq) const {
;         const int row0 = rowoff + u.pm * BM + wr * 64 + fr, col0 = u.pn * BM + wc * 32 + 4 * fq;
; #pragma unroll
;         for (int ai = 0; ai < 2; ++ai)
; #pragma unroll
;             for (int m = 0; m < 4; ++m) {
;                 const int row = row0 + ai * HALF + m * 16; float ss = 0.f;
; #pragma unroll
;                 for (int bj = 0; bj < 2; ++bj)
; #pragma unroll
;                     for (int n = 0; n < 2; ++n) {
;                         const int col = col0 + bj * HALF + n * 16;
;                         const f32x4 x = base4(row, col) + acc[ai][bj][m][n];
;                         ss += (x[0] * x[0] + x[1] * x[1]) + (x[2] * x[2] + x[3] * x[3]);
;                         if (FIRST && !dry) { u32x2 w; w.x = pk2(x[0], x[1]); w.y = pk2(x[2], x[3]); *(u32x2*)(XB + (size_t)row * DM + col) = w; }
;                     }
;                 ss += __shfl_xor(ss, 16); ss += __shfl_xor(ss, 32);
;                 if (fq == 0 && !dry) unsafeAtomicAdd(SS + row, ss);
	v_add_f32_e32 v220, v220, v221
	ds_bpermute_b32 v221, v153, v220
	s_waitcnt lgkmcnt(0)
	v_add_f32_e32 v220, v220, v221
	s_and_saveexec_b64 s[20:21], s[2:3]
	global_atomic_add_f32 v142, v220, s[46:47] offset:64
	s_or_b64 exec, exec, s[20:21]
	global_load_dwordx4 v[170:173], v140, s[98:99]
	global_load_dwordx4 v[174:177], v140, s[98:99] offset:64
	global_load_dwordx4 v[178:181], v140, s[98:99] offset:512
	global_load_dwordx4 v[182:185], v140, s[98:99] offset:576
	s_add_u32 s98, s98, 0x10000
	s_addc_u32 s99, s99, 0
	s_add_u32 s100, s100, 0x8000
	s_addc_u32 s101, s101, 0
	s_waitcnt vmcnt(22)
	v_pk_add_f32 v[188:189], v[94:95], v[188:189]
	v_pk_add_f32 v[186:187], v[92:93], v[186:187]
	v_cvt_pk_bf16_f32 v93, v188, v189
	v_cvt_pk_bf16_f32 v92, v186, v187
	global_store_dwordx2 v141, v[92:93], s[100:101]
	v_mul_f32_e32 v218, v187, v187
	v_mul_f32_e32 v219, v189, v189
	v_fmac_f32_e32 v218, v186, v186
	v_fmac_f32_e32 v219, v188, v188
	v_add_f32_e32 v220, v218, v219
	v_pk_add_f32 v[192:193], v[90:91], v[192:193]
	v_pk_add_f32 v[190:191], v[88:89], v[190:191]
	v_cvt_pk_bf16_f32 v89, v192, v193
	v_cvt_pk_bf16_f32 v88, v190, v191
	global_store_dwordx2 v141, v[88:89], s[100:101] offset:32
	v_mul_f32_e32 v218, v191, v191
	v_mul_f32_e32 v219, v193, v193
	v_fmac_f32_e32 v218, v190, v190
	v_fmac_f32_e32 v219, v192, v192
	v_add_f32_e32 v218, v218, v219
	v_add_f32_e32 v220, v220, v218
	v_pk_add_f32 v[196:197], v[86:87], v[196:197]
	v_pk_add_f32 v[194:195], v[84:85], v[194:195]
	v_cvt_pk_bf16_f32 v85, v196, v197
	v_cvt_pk_bf16_f32 v84, v194, v195
	global_store_dwordx2 v141, v[84:85], s[100:101] offset:256
	v_mul_f32_e32 v218, v195, v195
	v_mul_f32_e32 v219, v197, v197
	v_fmac_f32_e32 v218, v194, v194
	v_fmac_f32_e32 v219, v196, v196
	v_add_f32_e32 v218, v218, v219
	v_add_f32_e32 v220, v220, v218
	v_pk_add_f32 v[200:201], v[82:83], v[200:201]
	v_pk_add_f32 v[198:199], v[80:81], v[198:199]
	v_cvt_pk_bf16_f32 v81, v200, v201
	v_cvt_pk_bf16_f32 v80, v198, v199
	global_store_dwordx2 v141, v[80:81], s[100:101] offset:288
	v_mul_f32_e32 v218, v199, v199
	v_mul_f32_e32 v219, v201, v201
	v_fmac_f32_e32 v218, v198, v198
	v_fmac_f32_e32 v219, v200, v200
	v_add_f32_e32 v218, v218, v219
	v_add_f32_e32 v220, v220, v218
	ds_bpermute_b32 v221, v143, v220
	s_waitcnt lgkmcnt(0)
	v_add_f32_e32 v220, v220, v221
	ds_bpermute_b32 v221, v153, v220
	s_waitcnt lgkmcnt(0)
	v_add_f32_e32 v220, v220, v221
	s_and_saveexec_b64 s[20:21], s[2:3]
	global_atomic_add_f32 v142, v220, s[46:47] offset:128
	s_or_b64 exec, exec, s[20:21]
	global_load_dwordx4 v[186:189], v140, s[98:99]
	global_load_dwordx4 v[190:193], v140, s[98:99] offset:64
	global_load_dwordx4 v[194:197], v140, s[98:99] offset:512
	global_load_dwordx4 v[198:201], v140, s[98:99] offset:576
	s_add_u32 s98, s98, 0x10000
	s_addc_u32 s99, s99, 0
	s_add_u32 s100, s100, 0x8000
	s_addc_u32 s101, s101, 0
	s_waitcnt vmcnt(27)
	v_pk_add_f32 v[204:205], v[78:79], v[204:205]
	v_pk_add_f32 v[202:203], v[76:77], v[202:203]
	v_cvt_pk_bf16_f32 v77, v204, v205
	v_cvt_pk_bf16_f32 v76, v202, v203
	global_store_dwordx2 v141, v[76:77], s[100:101]
	v_mul_f32_e32 v218, v203, v203
	v_mul_f32_e32 v219, v205, v205
	v_fmac_f32_e32 v218, v202, v202
	v_fmac_f32_e32 v219, v204, v204
	v_add_f32_e32 v220, v218, v219
	v_pk_add_f32 v[208:209], v[74:75], v[208:209]
	v_pk_add_f32 v[206:207], v[72:73], v[206:207]
	v_cvt_pk_bf16_f32 v73, v208, v209
	v_cvt_pk_bf16_f32 v72, v206, v207
	global_store_dwordx2 v141, v[72:73], s[100:101] offset:32
	v_mul_f32_e32 v218, v207, v207
	v_mul_f32_e32 v219, v209, v209
	v_fmac_f32_e32 v218, v206, v206
	v_fmac_f32_e32 v219, v208, v208
	v_add_f32_e32 v218, v218, v219
	v_add_f32_e32 v220, v220, v218
	v_pk_add_f32 v[212:213], v[70:71], v[212:213]
	v_pk_add_f32 v[210:211], v[68:69], v[210:211]
	v_cvt_pk_bf16_f32 v69, v212, v213
	v_cvt_pk_bf16_f32 v68, v210, v211
	global_store_dwordx2 v141, v[68:69], s[100:101] offset:256
	v_mul_f32_e32 v218, v211, v211
	v_mul_f32_e32 v219, v213, v213
	v_fmac_f32_e32 v218, v210, v210
	v_fmac_f32_e32 v219, v212, v212
	v_add_f32_e32 v218, v218, v219
	v_add_f32_e32 v220, v220, v218
	v_pk_add_f32 v[216:217], v[66:67], v[216:217]
	v_pk_add_f32 v[214:215], v[64:65], v[214:215]
	v_cvt_pk_bf16_f32 v65, v216, v217
	v_cvt_pk_bf16_f32 v64, v214, v215
	global_store_dwordx2 v141, v[64:65], s[100:101] offset:288
	v_mul_f32_e32 v218, v215, v215
	v_mul_f32_e32 v219, v217, v217
	v_fmac_f32_e32 v218, v214, v214
	v_fmac_f32_e32 v219, v216, v216
	v_add_f32_e32 v218, v218, v219
	v_add_f32_e32 v220, v220, v218
	ds_bpermute_b32 v221, v143, v220
	s_waitcnt lgkmcnt(0)
	v_add_f32_e32 v220, v220, v221
	ds_bpermute_b32 v221, v153, v220
	s_waitcnt lgkmcnt(0)
	v_add_f32_e32 v220, v220, v221
	s_and_saveexec_b64 s[20:21], s[2:3]
	global_atomic_add_f32 v142, v220, s[46:47] offset:192
	s_or_b64 exec, exec, s[20:21]
	global_load_dwordx4 v[202:205], v140, s[98:99]
	global_load_dwordx4 v[206:209], v140, s[98:99] offset:64
	global_load_dwordx4 v[210:213], v140, s[98:99] offset:512
	global_load_dwordx4 v[214:217], v140, s[98:99] offset:576
	s_add_u32 s100, s100, 0x8000
	s_addc_u32 s101, s101, 0
	s_add_u32 s100, s100, 0x20000
	s_addc_u32 s101, s101, 0
	s_waitcnt vmcnt(27)
; DI unsigned pk2(float lo, float hi) { f32x2_t v = {lo, hi}; bf16x2_t b = __builtin_convertvector(v, bf16x2_t); return __builtin_bit_cast(unsigned, b); }
;     DI void operator()(AccRef acc, const Unit& u, int wr, int wc, int fr, int fq) const {
;     ...
;                 const int row = row0 + ai * HALF + m * 16; float ss = 0.f;
; #pragma unroll
;                 for (int bj = 0; bj < 2; ++bj)
; #pragma unroll
;                     for (int n = 0; n < 2; ++n) {
;                         const int col = col0 + bj * HALF + n * 16;
;                         const f32x4 x = base4(row, col) + acc[ai][bj][m][n];
;                         ss += (x[0] * x[0] + x[1] * x[1]) + (x[2] * x[2] + x[3] * x[3]);
;                         if (FIRST && !dry) { u32x2 w; w.x = pk2(x[0], x[1]); w.y = pk2(x[2], x[3]); *(u32x2*)(XB + (size_t)row * DM + col) = w; }
;                     }
;                 ss += __shfl_xor(ss, 16); ss += __shfl_xor(ss, 32);
;                 if (fq == 0 && !dry) unsafeAtomicAdd(SS + row, ss);
	v_pk_add_f32 v[156:157], v[62:63], v[156:157]
	v_pk_add_f32 v[154:155], v[60:61], v[154:155]
	v_cvt_pk_bf16_f32 v61, v156, v157
	v_cvt_pk_bf16_f32 v60, v154, v155
	global_store_dwordx2 v141, v[60:61], s[100:101]
	v_mul_f32_e32 v218, v155, v155
	v_mul_f32_e32 v219, v157, v157
	v_fmac_f32_e32 v218, v154, v154
	v_fmac_f32_e32 v219, v156, v156
	v_add_f32_e32 v220, v218, v219
	v_pk_add_f32 v[160:161], v[58:59], v[160:161]
	v_pk_add_f32 v[158:159], v[56:57], v[158:159]
	v_cvt_pk_bf16_f32 v57, v160, v161
	v_cvt_pk_bf16_f32 v56, v158, v159
	global_store_dwordx2 v141, v[56:57], s[100:101] offset:32
	v_mul_f32_e32 v218, v159, v159
	v_mul_f32_e32 v219, v161, v161
	v_fmac_f32_e32 v218, v158, v158
	v_fmac_f32_e32 v219, v160, v160
	v_add_f32_e32 v218, v218, v219
	v_add_f32_e32 v220, v220, v218
	v_pk_add_f32 v[164:165], v[54:55], v[164:165]
	v_pk_add_f32 v[162:163], v[52:53], v[162:163]
	v_cvt_pk_bf16_f32 v53, v164, v165
	v_cvt_pk_bf16_f32 v52, v162, v163
	global_store_dwordx2 v141, v[52:53], s[100:101] offset:256
	v_mul_f32_e32 v218, v163, v163
	v_mul_f32_e32 v219, v165, v165
	v_fmac_f32_e32 v218, v162, v162
	v_fmac_f32_e32 v219, v164, v164
	v_add_f32_e32 v218, v218, v219
	v_add_f32_e32 v220, v220, v218
	v_pk_add_f32 v[168:169], v[50:51], v[168:169]
	v_pk_add_f32 v[166:167], v[48:49], v[166:167]
	v_cvt_pk_bf16_f32 v49, v168, v169
	v_cvt_pk_bf16_f32 v48, v166, v167
	global_store_dwordx2 v141, v[48:49], s[100:101] offset:288
	v_mul_f32_e32 v218, v167, v167
	v_mul_f32_e32 v219, v169, v169
	v_fmac_f32_e32 v218, v166, v166
	v_fmac_f32_e32 v219, v168, v168
	v_add_f32_e32 v218, v218, v219
	v_add_f32_e32 v220, v220, v218
	ds_bpermute_b32 v221, v143, v220
	s_waitcnt lgkmcnt(0)
	v_add_f32_e32 v220, v220, v221
	ds_bpermute_b32 v221, v153, v220
	s_waitcnt lgkmcnt(0)
	v_add_f32_e32 v220, v220, v221
	s_and_saveexec_b64 s[20:21], s[2:3]
	global_atomic_add_f32 v142, v220, s[46:47] offset:512
	s_or_b64 exec, exec, s[20:21]
	s_add_u32 s100, s100, 0x8000
	s_addc_u32 s101, s101, 0
	s_waitcnt vmcnt(23)
	v_pk_add_f32 v[172:173], v[46:47], v[172:173]
	v_pk_add_f32 v[170:171], v[44:45], v[170:171]
	v_cvt_pk_bf16_f32 v45, v172, v173
	v_cvt_pk_bf16_f32 v44, v170, v171
	global_store_dwordx2 v141, v[44:45], s[100:101]
	v_mul_f32_e32 v218, v171, v171
	v_mul_f32_e32 v219, v173, v173
	v_fmac_f32_e32 v218, v170, v170
	v_fmac_f32_e32 v219, v172, v172
	v_add_f32_e32 v220, v218, v219
	v_pk_add_f32 v[176:177], v[42:43], v[176:177]
	v_pk_add_f32 v[174:175], v[40:41], v[174:175]
	v_cvt_pk_bf16_f32 v41, v176, v177
	v_cvt_pk_bf16_f32 v40, v174, v175
	global_store_dwordx2 v141, v[40:41], s[100:101] offset:32
	v_mul_f32_e32 v218, v175, v175
	v_mul_f32_e32 v219, v177, v177
	v_fmac_f32_e32 v218, v174, v174
	v_fmac_f32_e32 v219, v176, v176
	v_add_f32_e32 v218, v218, v219
	v_add_f32_e32 v220, v220, v218
	v_pk_add_f32 v[180:181], v[38:39], v[180:181]
	v_pk_add_f32 v[178:179], v[36:37], v[178:179]
	v_cvt_pk_bf16_f32 v37, v180, v181
	v_cvt_pk_bf16_f32 v36, v178, v179
	global_store_dwordx2 v141, v[36:37], s[100:101] offset:256
	v_mul_f32_e32 v218, v179, v179
	v_mul_f32_e32 v219, v181, v181
	v_fmac_f32_e32 v218, v178, v178
	v_fmac_f32_e32 v219, v180, v180
	v_add_f32_e32 v218, v218, v219
	v_add_f32_e32 v220, v220, v218
	v_pk_add_f32 v[184:185], v[34:35], v[184:185]
	v_pk_add_f32 v[182:183], v[32:33], v[182:183]
	v_cvt_pk_bf16_f32 v33, v184, v185
	v_cvt_pk_bf16_f32 v32, v182, v183
	global_store_dwordx2 v141, v[32:33], s[100:101] offset:288
	v_mul_f32_e32 v218, v183, v183
	v_mul_f32_e32 v219, v185, v185
	v_fmac_f32_e32 v218, v182, v182
	v_fmac_f32_e32 v219, v184, v184
	v_add_f32_e32 v218, v218, v219
	v_add_f32_e32 v220, v220, v218
	ds_bpermute_b32 v221, v143, v220
	s_waitcnt lgkmcnt(0)
	v_add_f32_e32 v220, v220, v221
	ds_bpermute_b32 v221, v153, v220
	s_waitcnt lgkmcnt(0)
	v_add_f32_e32 v220, v220, v221
	s_and_saveexec_b64 s[20:21], s[2:3]
	global_atomic_add_f32 v142, v220, s[46:47] offset:576
	s_or_b64 exec, exec, s[20:21]
	s_add_u32 s100, s100, 0x8000
	s_addc_u32 s101, s101, 0
	s_waitcnt vmcnt(19)
; DI unsigned pk2(float lo, float hi) { f32x2_t v = {lo, hi}; bf16x2_t b = __builtin_convertvector(v, bf16x2_t); return __builtin_bit_cast(unsigned, b); }
;     DI void operator()(AccRef acc, const Unit& u, int wr, int wc, int fr, int fq) const {
;     ...
;                 const int row = row0 + ai * HALF + m * 16; float ss = 0.f;
; #pragma unroll
;                 for (int bj = 0; bj < 2; ++bj)
; #pragma unroll
;                     for (int n = 0; n < 2; ++n) {
;                         const int col = col0 + bj * HALF + n * 16;
;                         const f32x4 x = base4(row, col) + acc[ai][bj][m][n];
;                         ss += (x[0] * x[0] + x[1] * x[1]) + (x[2] * x[2] + x[3] * x[3]);
;                         if (FIRST && !dry) { u32x2 w; w.x = pk2(x[0], x[1]); w.y = pk2(x[2], x[3]); *(u32x2*)(XB + (size_t)row * DM + col) = w; }
;                     }
;                 ss += __shfl_xor(ss, 16); ss += __shfl_xor(ss, 32);
;                 if (fq == 0 && !dry) unsafeAtomicAdd(SS + row, ss);
	v_pk_add_f32 v[188:189], v[30:31], v[188:189]
	v_pk_add_f32 v[186:187], v[28:29], v[186:187]
	v_cvt_pk_bf16_f32 v29, v188, v189
	v_cvt_pk_bf16_f32 v28, v186, v187
	global_store_dwordx2 v141, v[28:29], s[100:101]
	v_mul_f32_e32 v218, v187, v187
	v_mul_f32_e32 v219, v189, v189
	v_fmac_f32_e32 v218, v186, v186
	v_fmac_f32_e32 v219, v188, v188
	v_add_f32_e32 v220, v218, v219
	v_pk_add_f32 v[192:193], v[26:27], v[192:193]
	v_pk_add_f32 v[190:191], v[24:25], v[190:191]
	v_cvt_pk_bf16_f32 v25, v192, v193
	v_cvt_pk_bf16_f32 v24, v190, v191
	global_store_dwordx2 v141, v[24:25], s[100:101] offset:32
	v_mul_f32_e32 v218, v191, v191
	v_mul_f32_e32 v219, v193, v193
	v_fmac_f32_e32 v218, v190, v190
	v_fmac_f32_e32 v219, v192, v192
	v_add_f32_e32 v218, v218, v219
	v_add_f32_e32 v220, v220, v218
	v_pk_add_f32 v[196:197], v[22:23], v[196:197]
	v_pk_add_f32 v[194:195], v[20:21], v[194:195]
	v_cvt_pk_bf16_f32 v21, v196, v197
	v_cvt_pk_bf16_f32 v20, v194, v195
	global_store_dwordx2 v141, v[20:21], s[100:101] offset:256
	v_mul_f32_e32 v218, v195, v195
	v_mul_f32_e32 v219, v197, v197
	v_fmac_f32_e32 v218, v194, v194
	v_fmac_f32_e32 v219, v196, v196
	v_add_f32_e32 v218, v218, v219
	v_add_f32_e32 v220, v220, v218
	v_pk_add_f32 v[200:201], v[18:19], v[200:201]
	v_pk_add_f32 v[198:199], v[16:17], v[198:199]
	v_cvt_pk_bf16_f32 v17, v200, v201
	v_cvt_pk_bf16_f32 v16, v198, v199
	global_store_dwordx2 v141, v[16:17], s[100:101] offset:288
	v_mul_f32_e32 v218, v199, v199
	v_mul_f32_e32 v219, v201, v201
	v_fmac_f32_e32 v218, v198, v198
	v_fmac_f32_e32 v219, v200, v200
	v_add_f32_e32 v218, v218, v219
	v_add_f32_e32 v220, v220, v218
	ds_bpermute_b32 v221, v143, v220
	s_waitcnt lgkmcnt(0)
	v_add_f32_e32 v220, v220, v221
	ds_bpermute_b32 v221, v153, v220
	s_waitcnt lgkmcnt(0)
	v_add_f32_e32 v220, v220, v221
	s_and_saveexec_b64 s[20:21], s[2:3]
	global_atomic_add_f32 v142, v220, s[46:47] offset:640
	s_or_b64 exec, exec, s[20:21]
	s_add_u32 s100, s100, 0x8000
	s_addc_u32 s101, s101, 0
	s_waitcnt vmcnt(15)
	v_pk_add_f32 v[204:205], v[14:15], v[204:205]
	v_pk_add_f32 v[202:203], v[12:13], v[202:203]
	v_cvt_pk_bf16_f32 v13, v204, v205
	v_cvt_pk_bf16_f32 v12, v202, v203
	global_store_dwordx2 v141, v[12:13], s[100:101]
	v_mul_f32_e32 v218, v203, v203
	v_mul_f32_e32 v219, v205, v205
	v_fmac_f32_e32 v218, v202, v202
	v_fmac_f32_e32 v219, v204, v204
	v_add_f32_e32 v220, v218, v219
	v_pk_add_f32 v[208:209], v[10:11], v[208:209]
	v_pk_add_f32 v[206:207], v[8:9], v[206:207]
	v_cvt_pk_bf16_f32 v9, v208, v209
	v_cvt_pk_bf16_f32 v8, v206, v207
	global_store_dwordx2 v141, v[8:9], s[100:101] offset:32
	v_mul_f32_e32 v218, v207, v207
	v_mul_f32_e32 v219, v209, v209
	v_fmac_f32_e32 v218, v206, v206
	v_fmac_f32_e32 v219, v208, v208
	v_add_f32_e32 v218, v218, v219
	v_add_f32_e32 v220, v220, v218
	v_pk_add_f32 v[212:213], v[6:7], v[212:213]
	v_pk_add_f32 v[210:211], v[4:5], v[210:211]
	v_cvt_pk_bf16_f32 v5, v212, v213
	v_cvt_pk_bf16_f32 v4, v210, v211
	global_store_dwordx2 v141, v[4:5], s[100:101] offset:256
	v_mul_f32_e32 v218, v211, v211
	v_mul_f32_e32 v219, v213, v213
	v_fmac_f32_e32 v218, v210, v210
	v_fmac_f32_e32 v219, v212, v212
	v_add_f32_e32 v218, v218, v219
	v_add_f32_e32 v220, v220, v218
	v_pk_add_f32 v[216:217], v[2:3], v[216:217]
	v_pk_add_f32 v[214:215], v[0:1], v[214:215]
	v_cvt_pk_bf16_f32 v1, v216, v217
	v_cvt_pk_bf16_f32 v0, v214, v215
	global_store_dwordx2 v141, v[0:1], s[100:101] offset:288
	v_mul_f32_e32 v218, v215, v215
	v_mul_f32_e32 v219, v217, v217
	v_fmac_f32_e32 v218, v214, v214
	v_fmac_f32_e32 v219, v216, v216
	v_add_f32_e32 v218, v218, v219
	v_add_f32_e32 v220, v220, v218
	ds_bpermute_b32 v221, v143, v220
	s_waitcnt lgkmcnt(0)
	v_add_f32_e32 v220, v220, v221
	ds_bpermute_b32 v221, v153, v220
	s_waitcnt lgkmcnt(0)
	v_add_f32_e32 v220, v220, v221
	s_and_saveexec_b64 s[20:21], s[2:3]
	global_atomic_add_f32 v142, v220, s[46:47] offset:704
	s_or_b64 exec, exec, s[20:21]
	s_andn2_b64 vcc, exec, s[4:5]
	s_mov_b64 s[4:5], -1
	s_cbranch_vccnz .LBB0_1392
	s_andn2_b64 vcc, exec, s[6:7]
	s_cbranch_vccnz .LBB0_1391
	s_barrier
	s_branch .LBB0_1391
